# v11 + LayerNorm-fold loops of the background conversion items de-serialised (all loads of a loop body hoisted to its top into phase-dead registers, one wait)
# baseline (speedup 1.0000x reference)
; __device__ __forceinline__ float bf_round(float f) { return __uint_as_float(f2bf(f) << 16); }
; __device__ __forceinline__ void atomic_addq(i64* p, float v, float scale) { (void)__hip_atomic_fetch_add((unsigned long long*)p, (unsigned long long)(i64)__builtin_rintf(v * scale), __ATOMIC_RELAXED, __HIP_MEMORY_SCOPE_AGENT); }
; template <class Map>
; __device__ __forceinline__ void conv_item(const Frame& F, int it, const float* W, int K, int N, bf16_t* WT, const float* gk, int gmask, float gmul, const float* bk, i64* cs, i64* bw, Map map) {
;     ...
;             const int n = lane & 31, kh = lane >> 5; float sb = 0.f, sc = 0.f;
; #pragma unroll 8
;             for (int j = 0; j < 32; ++j) { const int kk = kh * 32 + j; const float w = scr[kk * 33 + n]; sb += bk[k0 + kk] * w; sc += bf_round(gk[(k0 + kk) & gmask] * gmul * w); }
;             { auto r = __builtin_amdgcn_permlane32_swap(__float_as_uint(sb), __float_as_uint(sb), false, false); sb = __uint_as_float(r[0]) + __uint_as_float(r[1]); }
;             { auto r = __builtin_amdgcn_permlane32_swap(__float_as_uint(sc), __float_as_uint(sc), false, false); sc = __uint_as_float(r[0]) + __uint_as_float(r[1]); }
;             if (lane < 32) { atomic_addq(bw + v0 + n, sb, FX_COL); atomic_addq(cs + v0 + n, sc, FX_COL); }
.LBB0_256:
	v_lshl_add_u64 v[132:133], v[6:7], 0, s[12:13]
	v_add_co_u32_e32 v132, vcc, 0x2000, v132
	v_addc_co_u32_e32 v133, vcc, 0, v133, vcc
	global_load_dwordx4 v[136:139], v[132:133], off
	v_lshl_add_u64 v[134:135], v[6:7], 0, s[12:13]
	v_lshl_add_u64 v[140:141], v[134:135], 0, s[92:93]
	global_load_dwordx4 v[144:147], v[140:141], off offset:16
	v_and_b32_e32 v142, 0x7f8, v18
	v_lshlrev_b32_e32 v142, 2, v142
	global_load_dword v143, v142, s[24:25]
	v_lshl_add_u64 v[148:149], v[4:5], 0, s[12:13]
	v_add_co_u32_e32 v148, vcc, s48, v148
	v_addc_co_u32_e32 v149, vcc, 0, v149, vcc
	global_load_dword v150, v[148:149], off offset:4
	v_add_u32_e32 v151, 2, v18
	v_and_b32_e32 v152, 0x7fa, v151
	v_lshlrev_b32_e32 v152, 2, v152
	global_load_dword v153, v152, s[24:25]
	v_lshl_add_u64 v[154:155], v[4:5], 0, s[12:13]
	v_add_co_u32_e32 v154, vcc, s48, v154
	v_addc_co_u32_e32 v155, vcc, 0, v155, vcc
	global_load_dword v156, v[154:155], off offset:12
	v_add_u32_e32 v157, 4, v18
	v_and_b32_e32 v158, 0x7fc, v157
	v_lshlrev_b32_e32 v158, 2, v158
	global_load_dword v159, v158, s[24:25]
	v_lshl_add_u64 v[160:161], v[4:5], 0, s[12:13]
	v_add_co_u32_e32 v160, vcc, s48, v160
	v_addc_co_u32_e32 v161, vcc, 0, v161, vcc
	global_load_dword v162, v[160:161], off offset:20
	v_add_u32_e32 v163, 6, v18
	v_and_b32_e32 v164, 0x7fe, v163
	v_lshlrev_b32_e32 v164, 2, v164
	global_load_dword v165, v164, s[24:25]
	v_lshl_add_u64 v[166:167], v[4:5], 0, s[12:13]
	v_add_co_u32_e32 v166, vcc, s48, v166
	v_addc_co_u32_e32 v167, vcc, 0, v167, vcc
	global_load_dword v168, v[166:167], off offset:28
	s_waitcnt vmcnt(0)
	v_lshl_add_u64 v[0:1], v[6:7], 0, s[12:13]
	v_lshl_add_u64 v[2:3], v[0:1], 0, s[92:93]
	v_add_co_u32_e32 v0, vcc, 0x2000, v0
	ds_read2_b32 v[24:25], v19 offset1:33
	s_nop 0
	v_addc_co_u32_e32 v1, vcc, 0, v1, vcc
	s_nop 0
	s_waitcnt vmcnt(1) lgkmcnt(0)
	v_mul_f32_e32 v26, v24, v136
	v_and_b32_e32 v20, 0x7f8, v18
	v_lshlrev_b32_e32 v20, 2, v20
	s_waitcnt vmcnt(0)
	v_mul_f32_e32 v20, v24, v143
	v_bfe_u32 v24, v20, 16, 1
	v_add3_u32 v20, v20, v24, s73
	v_and_b32_e32 v27, 0xffff0000, v20
	v_pk_add_f32 v[26:27], v[8:9], v[26:27]
	v_lshl_add_u64 v[8:9], v[4:5], 0, s[12:13]
	v_add_co_u32_e32 v8, vcc, s48, v8
	v_mul_f32_e32 v20, v25, v137
	s_nop 0
	v_addc_co_u32_e32 v9, vcc, 0, v9, vcc
	s_add_u32 s12, s12, 32
	s_addc_u32 s13, s13, 0
	s_cmpk_eq_i32 s12, 0x80
	s_waitcnt vmcnt(0)
	v_mul_f32_e32 v21, v25, v150
	v_bfe_u32 v24, v21, 16, 1
	v_add3_u32 v21, v21, v24, s73
	ds_read2_b32 v[24:25], v19 offset0:66 offset1:99
	v_and_b32_e32 v21, 0xffff0000, v21
	v_pk_add_f32 v[20:21], v[26:27], v[20:21]
	v_add_u32_e32 v27, 2, v18
	s_waitcnt lgkmcnt(0)
	v_mul_f32_e32 v26, v24, v138
	v_and_b32_e32 v22, 0x7fa, v27
	v_lshlrev_b32_e32 v22, 2, v22
	s_waitcnt vmcnt(0)
	v_mul_f32_e32 v22, v24, v153
	v_bfe_u32 v24, v22, 16, 1
	v_add3_u32 v22, v22, v24, s73
	v_and_b32_e32 v27, 0xffff0000, v22
	v_mul_f32_e32 v22, v25, v139
	v_pk_add_f32 v[20:21], v[20:21], v[26:27]
	s_waitcnt vmcnt(0)
	v_mul_f32_e32 v23, v25, v156
	v_bfe_u32 v24, v23, 16, 1
	v_add3_u32 v23, v23, v24, s73
	v_and_b32_e32 v23, 0xffff0000, v23
	v_pk_add_f32 v[20:21], v[20:21], v[22:23]
	ds_read2_b32 v[22:23], v19 offset0:132 offset1:165
	v_add_u32_e32 v25, 4, v18
	s_waitcnt lgkmcnt(0)
	v_mul_f32_e32 v24, v22, v144
	v_and_b32_e32 v0, 0x7fc, v25
	v_lshlrev_b32_e32 v0, 2, v0
	s_waitcnt vmcnt(0)
	v_mul_f32_e32 v0, v22, v159
	v_bfe_u32 v22, v0, 16, 1
	v_add3_u32 v0, v0, v22, s73
	v_and_b32_e32 v25, 0xffff0000, v0
	v_mul_f32_e32 v0, v23, v145
	v_pk_add_f32 v[20:21], v[20:21], v[24:25]
	s_waitcnt vmcnt(0)
	v_mul_f32_e32 v1, v23, v162
	v_bfe_u32 v22, v1, 16, 1
	v_add3_u32 v1, v1, v22, s73
	v_and_b32_e32 v1, 0xffff0000, v1
	v_pk_add_f32 v[0:1], v[20:21], v[0:1]
	ds_read2_b32 v[20:21], v19 offset0:198 offset1:231
	v_add_u32_e32 v23, 6, v18
	v_add_u32_e32 v19, 0x420, v19
	v_add_u32_e32 v18, 8, v18
	s_waitcnt lgkmcnt(0)
	v_mul_f32_e32 v22, v20, v146
	v_and_b32_e32 v2, 0x7fe, v23
	v_lshlrev_b32_e32 v2, 2, v2
	s_waitcnt vmcnt(0)
	v_mul_f32_e32 v2, v20, v165
	v_bfe_u32 v20, v2, 16, 1
	v_add3_u32 v2, v2, v20, s73
	v_and_b32_e32 v23, 0xffff0000, v2
	v_mul_f32_e32 v2, v21, v147
	v_pk_add_f32 v[0:1], v[0:1], v[22:23]
	s_waitcnt vmcnt(0)
	v_mul_f32_e32 v3, v21, v168
	v_bfe_u32 v8, v3, 16, 1
	v_add3_u32 v3, v3, v8, s73
	v_and_b32_e32 v3, 0xffff0000, v3
	v_pk_add_f32 v[8:9], v[0:1], v[2:3]
	s_cbranch_scc0 .LBB0_256
	v_mov_b32_e32 v0, v8
	v_mov_b32_e32 v1, v9
	s_nop 0
	v_permlane32_swap_b32_e32 v8, v0
	v_permlane32_swap_b32_e32 v9, v1
	v_cmp_gt_u32_e32 vcc, 32, v16
	s_and_saveexec_b64 s[12:13], vcc
	s_cbranch_execz .LBB0_259
	s_lshl_b64 s[48:49], s[58:59], 3
	s_add_u32 s40, s40, s48
	s_addc_u32 s41, s41, s49
	s_add_u32 s48, s26, s48
	v_add_f32_e32 v0, v8, v0
	s_addc_u32 s49, s27, s49
	s_lshl_b32 s78, s17, 3
	v_mul_f32_e32 v0, 0x4f800000, v0
	s_add_u32 s26, s40, s78
	v_rndne_f32_e32 v2, v0
	s_mov_b32 s40, 0x2f800000
	v_mul_f32_e64 v0, |v2|, s40
	s_addc_u32 s27, s41, 0
	v_floor_f32_e32 v0, v0
	s_mov_b32 s41, 0xcf800000
	v_add_f32_e32 v4, v9, v1
	v_fma_f32 v1, v0, s41, |v2|
	v_cvt_u32_f32_e32 v5, v1
	v_cvt_u32_f32_e32 v3, v0
	v_ashrrev_i32_e32 v6, 31, v2
	v_lshlrev_b32_e32 v184, 3, v17
	v_xor_b32_e32 v2, v5, v6
	v_xor_b32_e32 v3, v3, v6
	v_sub_co_u32_e32 v2, vcc, v2, v6
	v_lshl_add_u64 v[0:1], s[26:27], 0, v[184:185]
	s_nop 0
	v_subb_co_u32_e32 v3, vcc, v3, v6, vcc
	s_mov_b32 s26, 0x630000
	v_add_co_u32_e32 v0, vcc, s26, v0
	s_add_u32 s26, s48, s78
	s_nop 0
	v_addc_co_u32_e32 v1, vcc, 0, v1, vcc
	flat_atomic_add_x2 v[0:1], v[2:3]
	v_mul_f32_e32 v0, 0x4f800000, v4
	v_rndne_f32_e32 v2, v0
	v_mul_f32_e64 v0, |v2|, s40
	v_floor_f32_e32 v0, v0
	v_fma_f32 v1, v0, s41, |v2|
	v_cvt_u32_f32_e32 v4, v1
	v_cvt_u32_f32_e32 v3, v0
	v_ashrrev_i32_e32 v5, 31, v2
	s_addc_u32 s27, s49, 0
	v_xor_b32_e32 v2, v4, v5
	v_xor_b32_e32 v3, v3, v5
	v_sub_co_u32_e32 v2, vcc, v2, v5
	v_lshl_add_u64 v[0:1], s[26:27], 0, v[184:185]
	s_nop 0
	v_subb_co_u32_e32 v3, vcc, v3, v5, vcc
	v_add_co_u32_e32 v0, vcc, 0x62c000, v0
	s_nop 1
	v_addc_co_u32_e32 v1, vcc, 0, v1, vcc
	flat_atomic_add_x2 v[0:1], v[2:3]

; __device__ __forceinline__ float bf_round(float f) { return __uint_as_float(f2bf(f) << 16); }
; __device__ __forceinline__ void atomic_addq(i64* p, float v, float scale) { (void)__hip_atomic_fetch_add((unsigned long long*)p, (unsigned long long)(i64)__builtin_rintf(v * scale), __ATOMIC_RELAXED, __HIP_MEMORY_SCOPE_AGENT); }
; template <class Map>
; __device__ __forceinline__ void conv_item(const Frame& F, int it, const float* W, int K, int N, bf16_t* WT, const float* gk, int gmask, float gmul, const float* bk, i64* cs, i64* bw, Map map) {
;     ...
;             const int n = lane & 31, kh = lane >> 5; float sb = 0.f, sc = 0.f;
; #pragma unroll 8
;             for (int j = 0; j < 32; ++j) { const int kk = kh * 32 + j; const float w = scr[kk * 33 + n]; sb += bk[k0 + kk] * w; sc += bf_round(gk[(k0 + kk) & gmask] * gmul * w); }
;             { auto r = __builtin_amdgcn_permlane32_swap(__float_as_uint(sb), __float_as_uint(sb), false, false); sb = __uint_as_float(r[0]) + __uint_as_float(r[1]); }
;             { auto r = __builtin_amdgcn_permlane32_swap(__float_as_uint(sc), __float_as_uint(sc), false, false); sc = __uint_as_float(r[0]) + __uint_as_float(r[1]); }
;             if (lane < 32) { atomic_addq(bw + v0 + n, sb, FX_COL); atomic_addq(cs + v0 + n, sc, FX_COL); }
.LBB0_267:
	v_lshl_add_u64 v[132:133], v[4:5], 0, s[48:49]
	global_load_dword v134, v[132:133], off
	v_and_b32_e32 v135, 0x7f8, v19
	v_lshlrev_b32_e32 v135, 2, v135
	global_load_dword v136, v135, s[24:25]
	v_lshl_add_u64 v[138:139], v[6:7], 0, s[48:49]
	global_load_dwordx3 v[140:142], v[138:139], off offset:20
	v_lshl_add_u64 v[144:145], v[6:7], 0, s[48:49]
	global_load_dwordx4 v[148:151], v[144:145], off offset:4
	v_lshl_add_u64 v[146:147], v[8:9], 0, s[48:49]
	global_load_dword v137, v[146:147], off offset:4
	v_add_u32_e32 v143, 2, v19
	v_and_b32_e32 v143, 0x7fa, v143
	v_lshlrev_b32_e32 v143, 2, v143
	global_load_dword v152, v143, s[24:25]
	v_lshl_add_u64 v[154:155], v[8:9], 0, s[48:49]
	global_load_dword v153, v[154:155], off offset:12
	v_add_u32_e32 v156, 4, v19
	v_and_b32_e32 v156, 0x7fc, v156
	v_lshlrev_b32_e32 v156, 2, v156
	global_load_dword v157, v156, s[24:25]
	v_lshl_add_u64 v[158:159], v[8:9], 0, s[48:49]
	global_load_dword v160, v[158:159], off offset:20
	v_add_u32_e32 v161, 6, v19
	v_and_b32_e32 v162, 0x7fe, v161
	v_lshlrev_b32_e32 v162, 2, v162
	global_load_dword v163, v162, s[24:25]
	v_lshl_add_u64 v[164:165], v[8:9], 0, s[48:49]
	global_load_dword v166, v[164:165], off offset:28
	s_waitcnt vmcnt(0)
	v_lshl_add_u64 v[10:11], v[4:5], 0, s[48:49]
	ds_read2_b32 v[26:27], v20 offset1:33
	s_waitcnt vmcnt(0) lgkmcnt(0)
	v_mul_f32_e32 v10, v26, v134
	v_and_b32_e32 v2, 0x7f8, v19
	v_lshlrev_b32_e32 v2, 2, v2
	s_waitcnt vmcnt(0)
	v_mul_f32_e32 v2, v26, v136
	v_bfe_u32 v11, v2, 16, 1
	v_add3_u32 v2, v2, v11, s73
	v_and_b32_e32 v11, 0xffff0000, v2
	v_pk_add_f32 v[28:29], v[0:1], v[10:11]
	v_lshl_add_u64 v[10:11], v[6:7], 0, s[48:49]
	v_lshl_add_u64 v[10:11], v[8:9], 0, s[48:49]
	s_add_u32 s48, s48, 32
	s_addc_u32 s49, s49, 0
	s_cmpk_eq_i32 s48, 0x80
	s_waitcnt vmcnt(1)
	v_mul_f32_e32 v26, v27, v148
	s_waitcnt vmcnt(0)
	v_mul_f32_e32 v21, v27, v137
	v_bfe_u32 v22, v21, 16, 1
	v_add3_u32 v21, v21, v22, s73
	v_and_b32_e32 v27, 0xffff0000, v21
	v_add_u32_e32 v21, 2, v19
	v_and_b32_e32 v21, 0x7fa, v21
	v_lshlrev_b32_e32 v21, 2, v21
	v_pk_add_f32 v[26:27], v[28:29], v[26:27]
	ds_read2_b32 v[28:29], v20 offset0:66 offset1:99
	s_waitcnt lgkmcnt(0)
	v_mul_f32_e32 v22, v28, v149
	s_waitcnt vmcnt(0)
	v_mul_f32_e32 v21, v28, v152
	v_bfe_u32 v23, v21, 16, 1
	v_add3_u32 v21, v21, v23, s73
	v_and_b32_e32 v23, 0xffff0000, v21
	v_pk_add_f32 v[22:23], v[26:27], v[22:23]
	v_mul_f32_e32 v26, v29, v150
	s_waitcnt vmcnt(0)
	v_mul_f32_e32 v21, v29, v153
	v_bfe_u32 v24, v21, 16, 1
	v_add3_u32 v21, v21, v24, s73
	v_and_b32_e32 v27, 0xffff0000, v21
	v_add_u32_e32 v21, 4, v19
	v_and_b32_e32 v21, 0x7fc, v21
	v_lshlrev_b32_e32 v21, 2, v21
	v_pk_add_f32 v[22:23], v[22:23], v[26:27]
	ds_read2_b32 v[26:27], v20 offset0:132 offset1:165
	s_waitcnt lgkmcnt(0)
	v_mul_f32_e32 v24, v26, v151
	s_waitcnt vmcnt(0)
	v_mul_f32_e32 v21, v26, v157
	v_bfe_u32 v25, v21, 16, 1
	v_add3_u32 v21, v21, v25, s73
	v_and_b32_e32 v25, 0xffff0000, v21
	v_pk_add_f32 v[22:23], v[22:23], v[24:25]
	v_mul_f32_e32 v24, v27, v140
	s_waitcnt vmcnt(0)
	v_mul_f32_e32 v0, v27, v160
	v_bfe_u32 v21, v0, 16, 1
	v_add3_u32 v0, v0, v21, s73
	v_and_b32_e32 v25, 0xffff0000, v0
	v_pk_add_f32 v[22:23], v[22:23], v[24:25]
	ds_read2_b32 v[24:25], v20 offset0:198 offset1:231
	v_add_u32_e32 v21, 6, v19
	v_add_u32_e32 v19, 8, v19
	v_add_u32_e32 v20, 0x420, v20
	s_waitcnt lgkmcnt(0)
	v_mul_f32_e32 v0, v24, v141
	v_and_b32_e32 v1, 0x7fe, v21
	v_lshlrev_b32_e32 v1, 2, v1
	s_waitcnt vmcnt(0)
	v_mul_f32_e32 v1, v24, v163
	v_bfe_u32 v21, v1, 16, 1
	v_add3_u32 v1, v1, v21, s73
	v_and_b32_e32 v1, 0xffff0000, v1
	v_pk_add_f32 v[0:1], v[22:23], v[0:1]
	v_mul_f32_e32 v22, v25, v142
	s_waitcnt vmcnt(0)
	v_mul_f32_e32 v2, v25, v166
	v_bfe_u32 v10, v2, 16, 1
	v_add3_u32 v2, v2, v10, s73
	v_and_b32_e32 v23, 0xffff0000, v2
	v_pk_add_f32 v[0:1], v[0:1], v[22:23]
	s_cbranch_scc0 .LBB0_267
	v_mov_b32_e32 v2, v0
	v_mov_b32_e32 v4, v1
	s_nop 0
	v_permlane32_swap_b32_e32 v0, v2
	v_permlane32_swap_b32_e32 v1, v4
	v_cmp_gt_u32_e32 vcc, 32, v18
	s_and_saveexec_b64 s[16:17], vcc
	s_cbranch_execz .LBB0_270
	s_lshl_b64 s[48:49], s[58:59], 3
	s_add_u32 s92, s12, s48
	v_add_f32_e32 v0, v0, v2
	s_addc_u32 s93, s13, s49
	v_mul_f32_e32 v0, 0x4f800000, v0
	s_add_u32 s40, s40, s48
	v_rndne_f32_e32 v2, v0
	s_mov_b32 s48, 0x2f800000
	v_mul_f32_e64 v0, |v2|, s48
	s_addc_u32 s41, s41, s49
	v_floor_f32_e32 v0, v0
	s_mov_b32 s49, 0xcf800000
	v_add_f32_e32 v6, v1, v4
	v_fma_f32 v1, v0, s49, |v2|
	v_cvt_u32_f32_e32 v4, v0
	v_cvt_u32_f32_e32 v5, v1
	s_ashr_i32 s79, s78, 31
	s_lshl_b64 s[12:13], s[78:79], 3
	v_ashrrev_i32_e32 v2, 31, v2
	s_add_u32 s40, s40, s12
	v_xor_b32_e32 v7, v4, v2
	v_xor_b32_e32 v4, v5, v2
	s_addc_u32 s41, s41, s13
	v_lshlrev_b32_e32 v184, 3, v17
	v_sub_co_u32_e32 v4, vcc, v4, v2
	v_lshl_add_u64 v[0:1], s[40:41], 0, v[184:185]
	s_nop 0
	v_subb_co_u32_e32 v5, vcc, v7, v2, vcc
	s_mov_b32 s40, 0x616000
	v_add_co_u32_e32 v0, vcc, s40, v0
	s_add_u32 s12, s92, s12
	s_nop 0
	v_addc_co_u32_e32 v1, vcc, 0, v1, vcc
	flat_atomic_add_x2 v[0:1], v[4:5]
	v_mul_f32_e32 v0, 0x4f800000, v6
	v_rndne_f32_e32 v2, v0
	v_mul_f32_e64 v0, |v2|, s48
	v_floor_f32_e32 v0, v0
	v_fma_f32 v1, v0, s49, |v2|
	v_cvt_u32_f32_e32 v4, v0
	v_cvt_u32_f32_e32 v5, v1
	v_ashrrev_i32_e32 v2, 31, v2
	s_addc_u32 s13, s93, s13
	v_xor_b32_e32 v6, v4, v2
	v_xor_b32_e32 v4, v5, v2
	v_sub_co_u32_e32 v4, vcc, v4, v2
	v_lshl_add_u64 v[0:1], s[12:13], 0, v[184:185]
	s_nop 0
	v_subb_co_u32_e32 v5, vcc, v6, v2, vcc
	v_add_co_u32_e32 v0, vcc, 0x600000, v0
	s_nop 1
	v_addc_co_u32_e32 v1, vcc, 0, v1, vcc
	flat_atomic_add_x2 v[0:1], v[4:5]

; __device__ __forceinline__ float bf_round(float f) { return __uint_as_float(f2bf(f) << 16); }
; __device__ __forceinline__ void atomic_addq(i64* p, float v, float scale) { (void)__hip_atomic_fetch_add((unsigned long long*)p, (unsigned long long)(i64)__builtin_rintf(v * scale), __ATOMIC_RELAXED, __HIP_MEMORY_SCOPE_AGENT); }
; template <class Map>
; __device__ __forceinline__ void conv_item(const Frame& F, int it, const float* W, int K, int N, bf16_t* WT, const float* gk, int gmask, float gmul, const float* bk, i64* cs, i64* bw, Map map) {
;     ...
;             const int n = lane & 31, kh = lane >> 5; float sb = 0.f, sc = 0.f;
; #pragma unroll 8
;             for (int j = 0; j < 32; ++j) { const int kk = kh * 32 + j; const float w = scr[kk * 33 + n]; sb += bk[k0 + kk] * w; sc += bf_round(gk[(k0 + kk) & gmask] * gmul * w); }
;             { auto r = __builtin_amdgcn_permlane32_swap(__float_as_uint(sb), __float_as_uint(sb), false, false); sb = __uint_as_float(r[0]) + __uint_as_float(r[1]); }
;             { auto r = __builtin_amdgcn_permlane32_swap(__float_as_uint(sc), __float_as_uint(sc), false, false); sc = __uint_as_float(r[0]) + __uint_as_float(r[1]); }
;             if (lane < 32) { atomic_addq(bw + v0 + n, sb, FX_COL); atomic_addq(cs + v0 + n, sc, FX_COL); }
.LBB0_455:
	v_lshl_add_u64 v[132:133], v[6:7], 0, s[48:49]
	v_add_co_u32_e32 v132, vcc, 0x2000, v132
	v_addc_co_u32_e32 v133, vcc, 0, v133, vcc
	global_load_dwordx4 v[136:139], v[132:133], off
	v_lshl_add_u64 v[134:135], v[6:7], 0, s[48:49]
	v_lshl_add_u64 v[140:141], v[134:135], 0, s[86:87]
	global_load_dwordx4 v[144:147], v[140:141], off offset:16
	v_and_b32_e32 v142, 0x7f8, v17
	v_lshlrev_b32_e32 v142, 2, v142
	global_load_dword v143, v142, s[84:85]
	v_lshl_add_u64 v[148:149], v[4:5], 0, s[48:49]
	v_add_co_u32_e32 v148, vcc, s16, v148
	v_addc_co_u32_e32 v149, vcc, 0, v149, vcc
	global_load_dword v150, v[148:149], off offset:4
	v_add_u32_e32 v151, 2, v17
	v_and_b32_e32 v151, 0x7fa, v151
	v_lshlrev_b32_e32 v151, 2, v151
	global_load_dword v152, v151, s[84:85]
	v_lshl_add_u64 v[154:155], v[4:5], 0, s[48:49]
	v_add_co_u32_e32 v154, vcc, s16, v154
	v_addc_co_u32_e32 v155, vcc, 0, v155, vcc
	global_load_dword v153, v[154:155], off offset:12
	v_add_u32_e32 v156, 4, v17
	v_and_b32_e32 v157, 0x7fc, v156
	v_lshlrev_b32_e32 v157, 2, v157
	global_load_dword v158, v157, s[84:85]
	v_lshl_add_u64 v[160:161], v[4:5], 0, s[48:49]
	v_add_co_u32_e32 v160, vcc, s16, v160
	v_addc_co_u32_e32 v161, vcc, 0, v161, vcc
	global_load_dword v159, v[160:161], off offset:20
	v_add_u32_e32 v162, 6, v17
	v_and_b32_e32 v163, 0x7fe, v162
	v_lshlrev_b32_e32 v163, 2, v163
	global_load_dword v164, v163, s[84:85]
	v_lshl_add_u64 v[166:167], v[4:5], 0, s[48:49]
	v_add_co_u32_e32 v166, vcc, s16, v166
	v_addc_co_u32_e32 v167, vcc, 0, v167, vcc
	global_load_dword v165, v[166:167], off offset:28
	s_waitcnt vmcnt(0)
	v_lshl_add_u64 v[0:1], v[6:7], 0, s[48:49]
	v_lshl_add_u64 v[2:3], v[0:1], 0, s[86:87]
	v_add_co_u32_e32 v0, vcc, 0x2000, v0
	v_and_b32_e32 v27, 0x7f8, v17
	s_nop 0
	v_addc_co_u32_e32 v1, vcc, 0, v1, vcc
	v_lshlrev_b32_e32 v27, 2, v27
	ds_read2_b32 v[32:33], v26 offset1:33
	s_nop 0
	s_waitcnt vmcnt(1) lgkmcnt(0)
	v_mul_f32_e32 v34, v32, v136
	s_waitcnt vmcnt(0)
	v_mul_f32_e32 v27, v32, v143
	v_bfe_u32 v28, v27, 16, 1
	v_add3_u32 v27, v27, v28, s73
	v_and_b32_e32 v35, 0xffff0000, v27
	v_pk_add_f32 v[34:35], v[8:9], v[34:35]
	v_lshl_add_u64 v[8:9], v[4:5], 0, s[48:49]
	v_add_co_u32_e32 v8, vcc, s16, v8
	v_mul_f32_e32 v28, v33, v137
	s_nop 0
	v_addc_co_u32_e32 v9, vcc, 0, v9, vcc
	s_add_u32 s48, s48, 32
	s_addc_u32 s49, s49, 0
	s_cmpk_eq_i32 s48, 0x80
	s_waitcnt vmcnt(0)
	v_mul_f32_e32 v27, v33, v150
	v_bfe_u32 v29, v27, 16, 1
	v_add3_u32 v27, v27, v29, s73
	v_and_b32_e32 v29, 0xffff0000, v27
	v_add_u32_e32 v27, 2, v17
	v_and_b32_e32 v27, 0x7fa, v27
	v_lshlrev_b32_e32 v27, 2, v27
	ds_read2_b32 v[32:33], v26 offset0:66 offset1:99
	v_pk_add_f32 v[28:29], v[34:35], v[28:29]
	s_waitcnt lgkmcnt(0)
	v_mul_f32_e32 v34, v32, v138
	s_waitcnt vmcnt(0)
	v_mul_f32_e32 v27, v32, v152
	v_bfe_u32 v30, v27, 16, 1
	v_add3_u32 v27, v27, v30, s73
	v_and_b32_e32 v35, 0xffff0000, v27
	v_mul_f32_e32 v30, v33, v139
	v_pk_add_f32 v[28:29], v[28:29], v[34:35]
	s_waitcnt vmcnt(0)
	v_mul_f32_e32 v27, v33, v153
	v_bfe_u32 v31, v27, 16, 1
	v_add3_u32 v27, v27, v31, s73
	v_and_b32_e32 v31, 0xffff0000, v27
	v_pk_add_f32 v[28:29], v[28:29], v[30:31]
	ds_read2_b32 v[30:31], v26 offset0:132 offset1:165
	v_add_u32_e32 v27, 4, v17
	s_waitcnt lgkmcnt(0)
	v_mul_f32_e32 v32, v30, v144
	v_and_b32_e32 v0, 0x7fc, v27
	v_lshlrev_b32_e32 v0, 2, v0
	s_waitcnt vmcnt(0)
	v_mul_f32_e32 v0, v30, v158
	v_bfe_u32 v27, v0, 16, 1
	v_add3_u32 v0, v0, v27, s73
	v_and_b32_e32 v33, 0xffff0000, v0
	v_mul_f32_e32 v0, v31, v145
	v_pk_add_f32 v[28:29], v[28:29], v[32:33]
	s_waitcnt vmcnt(0)
	v_mul_f32_e32 v1, v31, v159
	v_bfe_u32 v27, v1, 16, 1
	v_add3_u32 v1, v1, v27, s73
	v_and_b32_e32 v1, 0xffff0000, v1
	v_pk_add_f32 v[0:1], v[28:29], v[0:1]
	ds_read2_b32 v[28:29], v26 offset0:198 offset1:231
	v_add_u32_e32 v27, 6, v17
	v_add_u32_e32 v26, 0x420, v26
	v_add_u32_e32 v17, 8, v17
	s_waitcnt lgkmcnt(0)
	v_mul_f32_e32 v30, v28, v146
	v_and_b32_e32 v2, 0x7fe, v27
	v_lshlrev_b32_e32 v2, 2, v2
	s_waitcnt vmcnt(0)
	v_mul_f32_e32 v2, v28, v164
	v_bfe_u32 v27, v2, 16, 1
	v_add3_u32 v2, v2, v27, s73
	v_and_b32_e32 v31, 0xffff0000, v2
	v_mul_f32_e32 v2, v29, v147
	v_pk_add_f32 v[0:1], v[0:1], v[30:31]
	s_waitcnt vmcnt(0)
	v_mul_f32_e32 v3, v29, v165
	v_bfe_u32 v8, v3, 16, 1
	v_add3_u32 v3, v3, v8, s73
	v_and_b32_e32 v3, 0xffff0000, v3
	v_pk_add_f32 v[8:9], v[0:1], v[2:3]
	s_cbranch_scc0 .LBB0_455
	v_mov_b32_e32 v0, v8
	v_mov_b32_e32 v1, v9
	s_nop 0
	v_permlane32_swap_b32_e32 v8, v0
	v_permlane32_swap_b32_e32 v9, v1
	v_cmp_gt_u32_e32 vcc, 32, v15
	s_and_saveexec_b64 s[16:17], vcc
	s_cbranch_execz .LBB0_458
	s_lshl_b64 s[48:49], s[56:57], 3
	s_add_u32 s40, s40, s48
	v_add_f32_e32 v4, v8, v0
	s_addc_u32 s41, s41, s49
	v_lshlrev_b32_e32 v184, 3, v12
	v_mul_f32_e32 v4, 0x4f800000, v4
	v_add_f32_e32 v6, v9, v1
	v_lshl_add_u64 v[0:1], s[40:41], 0, v[184:185]
	v_rndne_f32_e32 v4, v4
	s_mov_b32 s40, 0x2f800000
	v_mul_f32_e64 v5, |v4|, s40
	v_floor_f32_e32 v5, v5
	s_mov_b32 s41, 0xcf800000
	v_fma_f32 v7, v5, s41, |v4|
	v_cvt_u32_f32_e32 v7, v7
	v_cvt_u32_f32_e32 v5, v5
	v_ashrrev_i32_e32 v8, 31, v4
	v_lshlrev_b32_e32 v2, 3, v16
	v_xor_b32_e32 v4, v7, v8
	v_mov_b32_e32 v3, v185
	v_xor_b32_e32 v5, v5, v8
	v_sub_co_u32_e32 v4, vcc, v4, v8
	s_add_u32 s12, s12, s48
	v_lshl_add_u64 v[0:1], v[0:1], 0, v[2:3]
	v_subb_co_u32_e32 v5, vcc, v5, v8, vcc
	s_mov_b32 s48, 0x630000
	v_add_co_u32_e32 v0, vcc, s48, v0
	s_addc_u32 s13, s13, s49
	s_nop 0
	v_addc_co_u32_e32 v1, vcc, 0, v1, vcc
	flat_atomic_add_x2 v[0:1], v[4:5]
	v_lshl_add_u64 v[0:1], s[12:13], 0, v[184:185]
	v_lshl_add_u64 v[0:1], v[0:1], 0, v[2:3]
	v_mul_f32_e32 v2, 0x4f800000, v6
	v_rndne_f32_e32 v2, v2
	v_mul_f32_e64 v3, |v2|, s40
	v_floor_f32_e32 v3, v3
	v_fma_f32 v4, v3, s41, |v2|
	v_cvt_u32_f32_e32 v4, v4
	v_cvt_u32_f32_e32 v3, v3
	v_ashrrev_i32_e32 v5, 31, v2
	v_xor_b32_e32 v2, v4, v5
	v_xor_b32_e32 v3, v3, v5
	v_sub_co_u32_e32 v2, vcc, v2, v5
	s_nop 1
	v_subb_co_u32_e32 v3, vcc, v3, v5, vcc
	v_add_co_u32_e32 v0, vcc, 0x62c000, v0
	s_nop 1
	v_addc_co_u32_e32 v1, vcc, 0, v1, vcc
	flat_atomic_add_x2 v[0:1], v[2:3]

; __device__ __forceinline__ float bf_round(float f) { return __uint_as_float(f2bf(f) << 16); }
; __device__ __forceinline__ void atomic_addq(i64* p, float v, float scale) { (void)__hip_atomic_fetch_add((unsigned long long*)p, (unsigned long long)(i64)__builtin_rintf(v * scale), __ATOMIC_RELAXED, __HIP_MEMORY_SCOPE_AGENT); }
; template <class Map>
; __device__ __forceinline__ void conv_item(const Frame& F, int it, const float* W, int K, int N, bf16_t* WT, const float* gk, int gmask, float gmul, const float* bk, i64* cs, i64* bw, Map map) {
;     ...
;             const int n = lane & 31, kh = lane >> 5; float sb = 0.f, sc = 0.f;
; #pragma unroll 8
;             for (int j = 0; j < 32; ++j) { const int kk = kh * 32 + j; const float w = scr[kk * 33 + n]; sb += bk[k0 + kk] * w; sc += bf_round(gk[(k0 + kk) & gmask] * gmul * w); }
;             { auto r = __builtin_amdgcn_permlane32_swap(__float_as_uint(sb), __float_as_uint(sb), false, false); sb = __uint_as_float(r[0]) + __uint_as_float(r[1]); }
;             { auto r = __builtin_amdgcn_permlane32_swap(__float_as_uint(sc), __float_as_uint(sc), false, false); sc = __uint_as_float(r[0]) + __uint_as_float(r[1]); }
;             if (lane < 32) { atomic_addq(bw + v0 + n, sb, FX_COL); atomic_addq(cs + v0 + n, sc, FX_COL); }
.LBB0_466:
	v_lshl_add_u64 v[132:133], v[6:7], 0, s[12:13]
	global_load_dword v134, v[132:133], off
	v_and_b32_e32 v135, 0x7f8, v26
	v_lshlrev_b32_e32 v135, 2, v135
	global_load_dword v136, v135, s[86:87]
	v_lshl_add_u64 v[138:139], v[8:9], 0, s[12:13]
	global_load_dwordx3 v[140:142], v[138:139], off offset:20
	v_lshl_add_u64 v[144:145], v[8:9], 0, s[12:13]
	global_load_dwordx4 v[148:151], v[144:145], off offset:4
	v_lshl_add_u64 v[146:147], v[10:11], 0, s[12:13]
	global_load_dword v137, v[146:147], off offset:4
	v_add_u32_e32 v143, 2, v26
	v_and_b32_e32 v152, 0x7fa, v143
	v_lshlrev_b32_e32 v152, 2, v152
	global_load_dword v153, v152, s[86:87]
	v_lshl_add_u64 v[154:155], v[10:11], 0, s[12:13]
	global_load_dword v156, v[154:155], off offset:12
	v_add_u32_e32 v157, 4, v26
	v_and_b32_e32 v158, 0x7fc, v157
	v_lshlrev_b32_e32 v158, 2, v158
	global_load_dword v159, v158, s[86:87]
	v_lshl_add_u64 v[160:161], v[10:11], 0, s[12:13]
	global_load_dword v162, v[160:161], off offset:20
	v_add_u32_e32 v163, 6, v26
	v_and_b32_e32 v164, 0x7fe, v163
	v_lshlrev_b32_e32 v164, 2, v164
	global_load_dword v165, v164, s[86:87]
	v_lshl_add_u64 v[166:167], v[10:11], 0, s[12:13]
	global_load_dword v168, v[166:167], off offset:28
	s_waitcnt vmcnt(0)
	v_lshl_add_u64 v[12:13], v[6:7], 0, s[12:13]
	ds_read2_b32 v[32:33], v27 offset1:33
	v_add_u32_e32 v36, 2, v26
	s_waitcnt vmcnt(0) lgkmcnt(0)
	v_mul_f32_e32 v12, v32, v134
	v_and_b32_e32 v2, 0x7f8, v26
	v_lshlrev_b32_e32 v2, 2, v2
	s_waitcnt vmcnt(0)
	v_mul_f32_e32 v2, v32, v136
	v_bfe_u32 v13, v2, 16, 1
	v_add3_u32 v2, v2, v13, s73
	v_and_b32_e32 v13, 0xffff0000, v2
	v_pk_add_f32 v[34:35], v[0:1], v[12:13]
	v_lshl_add_u64 v[12:13], v[8:9], 0, s[12:13]
	v_lshl_add_u64 v[12:13], v[10:11], 0, s[12:13]
	s_add_u32 s12, s12, 32
	s_addc_u32 s13, s13, 0
	s_cmpk_eq_i32 s12, 0x80
	s_waitcnt vmcnt(0)
	v_mul_f32_e32 v32, v33, v148
	s_waitcnt vmcnt(0)
	v_mul_f32_e32 v28, v33, v137
	v_bfe_u32 v33, v28, 16, 1
	v_add3_u32 v28, v28, v33, s73
	v_and_b32_e32 v33, 0xffff0000, v28
	v_pk_add_f32 v[32:33], v[34:35], v[32:33]
	ds_read2_b32 v[34:35], v27 offset0:66 offset1:99
	s_waitcnt lgkmcnt(0)
	v_mul_f32_e32 v28, v34, v149
	v_and_b32_e32 v29, 0x7fa, v36
	v_lshlrev_b32_e32 v29, 2, v29
	s_waitcnt vmcnt(0)
	v_mul_f32_e32 v29, v34, v153
	v_bfe_u32 v34, v29, 16, 1
	v_add3_u32 v29, v29, v34, s73
	v_and_b32_e32 v29, 0xffff0000, v29
	v_pk_add_f32 v[28:29], v[32:33], v[28:29]
	v_mul_f32_e32 v32, v35, v150
	v_add_u32_e32 v34, 4, v26
	s_waitcnt vmcnt(0)
	v_mul_f32_e32 v30, v35, v156
	v_bfe_u32 v33, v30, 16, 1
	v_add3_u32 v30, v30, v33, s73
	v_and_b32_e32 v33, 0xffff0000, v30
	v_pk_add_f32 v[28:29], v[28:29], v[32:33]
	ds_read2_b32 v[32:33], v27 offset0:132 offset1:165
	s_waitcnt lgkmcnt(0)
	v_mul_f32_e32 v30, v32, v151
	v_and_b32_e32 v31, 0x7fc, v34
	v_lshlrev_b32_e32 v31, 2, v31
	s_waitcnt vmcnt(0)
	v_mul_f32_e32 v31, v32, v159
	v_bfe_u32 v32, v31, 16, 1
	v_add3_u32 v31, v31, v32, s73
	v_and_b32_e32 v31, 0xffff0000, v31
	v_pk_add_f32 v[28:29], v[28:29], v[30:31]
	v_mul_f32_e32 v30, v33, v140
	v_add_u32_e32 v32, 6, v26
	v_add_u32_e32 v26, 8, v26
	s_waitcnt vmcnt(0)
	v_mul_f32_e32 v0, v33, v162
	v_bfe_u32 v31, v0, 16, 1
	v_add3_u32 v0, v0, v31, s73
	v_and_b32_e32 v31, 0xffff0000, v0
	v_pk_add_f32 v[28:29], v[28:29], v[30:31]
	ds_read2_b32 v[30:31], v27 offset0:198 offset1:231
	v_add_u32_e32 v27, 0x420, v27
	s_waitcnt lgkmcnt(0)
	v_mul_f32_e32 v0, v30, v141
	v_and_b32_e32 v1, 0x7fe, v32
	v_lshlrev_b32_e32 v1, 2, v1
	s_waitcnt vmcnt(0)
	v_mul_f32_e32 v1, v30, v165
	v_bfe_u32 v30, v1, 16, 1
	v_add3_u32 v1, v1, v30, s73
	v_and_b32_e32 v1, 0xffff0000, v1
	v_pk_add_f32 v[0:1], v[28:29], v[0:1]
	v_mul_f32_e32 v28, v31, v142
	s_waitcnt vmcnt(0)
	v_mul_f32_e32 v2, v31, v168
	v_bfe_u32 v12, v2, 16, 1
	v_add3_u32 v2, v2, v12, s73
	v_and_b32_e32 v29, 0xffff0000, v2
	v_pk_add_f32 v[0:1], v[0:1], v[28:29]
	s_cbranch_scc0 .LBB0_466
	v_mov_b32_e32 v2, v0
	v_mov_b32_e32 v6, v1
	s_nop 0
	v_permlane32_swap_b32_e32 v0, v2
	v_permlane32_swap_b32_e32 v1, v6
	v_cmp_gt_u32_e32 vcc, 32, v5
	s_and_saveexec_b64 s[12:13], vcc
	s_cbranch_execz .LBB0_469
	s_lshl_b64 s[16:17], s[56:57], 3
	s_add_u32 s38, s48, s16
	s_addc_u32 s39, s49, s17
	s_add_u32 s16, s40, s16
	v_add_f32_e32 v2, v0, v2
	v_ashrrev_i32_e32 v5, 31, v4
	s_addc_u32 s17, s41, s17
	v_add_f32_e32 v10, v1, v6
	v_lshlrev_b64 v[0:1], 3, v[4:5]
	v_mul_f32_e32 v2, 0x4f800000, v2
	v_lshl_add_u64 v[6:7], s[16:17], 0, v[0:1]
	v_rndne_f32_e32 v2, v2
	s_mov_b32 s16, 0x2f800000
	v_mul_f32_e64 v5, |v2|, s16
	v_floor_f32_e32 v5, v5
	s_mov_b32 s17, 0xcf800000
	v_fma_f32 v8, v5, s17, |v2|
	v_cvt_u32_f32_e32 v8, v8
	v_cvt_u32_f32_e32 v5, v5
	v_ashrrev_i32_e32 v2, 31, v2
	v_lshlrev_b32_e32 v184, 3, v25
	v_xor_b32_e32 v8, v8, v2
	v_xor_b32_e32 v5, v5, v2
	v_sub_co_u32_e32 v8, vcc, v8, v2
	v_lshl_add_u64 v[6:7], v[6:7], 0, v[184:185]
	s_nop 0
	v_subb_co_u32_e32 v9, vcc, v5, v2, vcc
	v_mul_f32_e32 v2, 0x4f800000, v10
	s_mov_b32 s40, 0x616000
	v_rndne_f32_e32 v2, v2
	v_add_co_u32_e32 v6, vcc, s40, v6
	v_mul_f32_e64 v5, |v2|, s16
	s_nop 0
	v_addc_co_u32_e32 v7, vcc, 0, v7, vcc
	v_floor_f32_e32 v5, v5
	flat_atomic_add_x2 v[6:7], v[8:9]
	v_fma_f32 v6, v5, s17, |v2|
	v_cvt_u32_f32_e32 v6, v6
	v_cvt_u32_f32_e32 v5, v5
	v_ashrrev_i32_e32 v2, 31, v2
	v_lshl_add_u64 v[0:1], s[38:39], 0, v[0:1]
	v_xor_b32_e32 v6, v6, v2
	v_xor_b32_e32 v5, v5, v2
	v_sub_co_u32_e32 v6, vcc, v6, v2
	v_lshl_add_u64 v[0:1], v[0:1], 0, v[184:185]
	s_nop 0
	v_subb_co_u32_e32 v7, vcc, v5, v2, vcc
	v_add_co_u32_e32 v0, vcc, 0x600000, v0
	s_nop 1
	v_addc_co_u32_e32 v1, vcc, 0, v1, vcc
	flat_atomic_add_x2 v[0:1], v[6:7]

; __device__ __forceinline__ float bf_round(float f) { return __uint_as_float(f2bf(f) << 16); }
; __device__ __forceinline__ void atomic_addq(i64* p, float v, float scale) { (void)__hip_atomic_fetch_add((unsigned long long*)p, (unsigned long long)(i64)__builtin_rintf(v * scale), __ATOMIC_RELAXED, __HIP_MEMORY_SCOPE_AGENT); }
; template <class Map>
; __device__ __forceinline__ void conv_item(const Frame& F, int it, const float* W, int K, int N, bf16_t* WT, const float* gk, int gmask, float gmul, const float* bk, i64* cs, i64* bw, Map map) {
;     ...
;             const int n = lane & 31, kh = lane >> 5; float sb = 0.f, sc = 0.f;
; #pragma unroll 8
;             for (int j = 0; j < 32; ++j) { const int kk = kh * 32 + j; const float w = scr[kk * 33 + n]; sb += bk[k0 + kk] * w; sc += bf_round(gk[(k0 + kk) & gmask] * gmul * w); }
;             { auto r = __builtin_amdgcn_permlane32_swap(__float_as_uint(sb), __float_as_uint(sb), false, false); sb = __uint_as_float(r[0]) + __uint_as_float(r[1]); }
;             { auto r = __builtin_amdgcn_permlane32_swap(__float_as_uint(sc), __float_as_uint(sc), false, false); sc = __uint_as_float(r[0]) + __uint_as_float(r[1]); }
;             if (lane < 32) { atomic_addq(bw + v0 + n, sb, FX_COL); atomic_addq(cs + v0 + n, sc, FX_COL); }
.LBB0_659:
	v_lshl_add_u64 v[132:133], v[6:7], 0, s[12:13]
	v_add_co_u32_e32 v132, vcc, 0x2000, v132
	v_addc_co_u32_e32 v133, vcc, 0, v133, vcc
	global_load_dwordx4 v[136:139], v[132:133], off
	v_lshl_add_u64 v[134:135], v[6:7], 0, s[12:13]
	v_lshl_add_u64 v[140:141], v[134:135], 0, s[74:75]
	global_load_dwordx4 v[144:147], v[140:141], off offset:16
	v_and_b32_e32 v142, 0x7f8, v19
	v_lshlrev_b32_e32 v142, 2, v142
	global_load_dword v143, v142, s[26:27]
	v_lshl_add_u64 v[148:149], v[4:5], 0, s[12:13]
	v_add_co_u32_e32 v148, vcc, s48, v148
	v_addc_co_u32_e32 v149, vcc, 0, v149, vcc
	global_load_dword v150, v[148:149], off offset:4
	v_add_u32_e32 v151, 2, v19
	v_and_b32_e32 v151, 0x7fa, v151
	v_lshlrev_b32_e32 v151, 2, v151
	global_load_dword v152, v151, s[26:27]
	v_lshl_add_u64 v[154:155], v[4:5], 0, s[12:13]
	v_add_co_u32_e32 v154, vcc, s48, v154
	v_addc_co_u32_e32 v155, vcc, 0, v155, vcc
	global_load_dword v153, v[154:155], off offset:12
	v_add_u32_e32 v156, 4, v19
	v_and_b32_e32 v157, 0x7fc, v156
	v_lshlrev_b32_e32 v157, 2, v157
	global_load_dword v158, v157, s[26:27]
	v_lshl_add_u64 v[160:161], v[4:5], 0, s[12:13]
	v_add_co_u32_e32 v160, vcc, s48, v160
	v_addc_co_u32_e32 v161, vcc, 0, v161, vcc
	global_load_dword v159, v[160:161], off offset:20
	v_add_u32_e32 v162, 6, v19
	v_and_b32_e32 v163, 0x7fe, v162
	v_lshlrev_b32_e32 v163, 2, v163
	global_load_dword v164, v163, s[26:27]
	v_lshl_add_u64 v[166:167], v[4:5], 0, s[12:13]
	v_add_co_u32_e32 v166, vcc, s48, v166
	v_addc_co_u32_e32 v167, vcc, 0, v167, vcc
	global_load_dword v165, v[166:167], off offset:28
	s_waitcnt vmcnt(0)
	v_lshl_add_u64 v[0:1], v[6:7], 0, s[12:13]
	v_lshl_add_u64 v[2:3], v[0:1], 0, s[74:75]
	v_add_co_u32_e32 v0, vcc, 0x2000, v0
	v_and_b32_e32 v21, 0x7f8, v19
	s_nop 0
	v_addc_co_u32_e32 v1, vcc, 0, v1, vcc
	v_lshlrev_b32_e32 v21, 2, v21
	ds_read2_b32 v[26:27], v20 offset1:33
	s_nop 0
	s_waitcnt vmcnt(1) lgkmcnt(0)
	v_mul_f32_e32 v28, v26, v136
	s_waitcnt vmcnt(0)
	v_mul_f32_e32 v21, v26, v143
	v_bfe_u32 v22, v21, 16, 1
	v_add3_u32 v21, v21, v22, s73
	v_and_b32_e32 v29, 0xffff0000, v21
	v_pk_add_f32 v[28:29], v[8:9], v[28:29]
	v_lshl_add_u64 v[8:9], v[4:5], 0, s[12:13]
	v_add_co_u32_e32 v8, vcc, s48, v8
	v_mul_f32_e32 v22, v27, v137
	s_nop 0
	v_addc_co_u32_e32 v9, vcc, 0, v9, vcc
	s_add_u32 s12, s12, 32
	s_addc_u32 s13, s13, 0
	s_cmpk_eq_i32 s12, 0x80
	s_waitcnt vmcnt(0)
	v_mul_f32_e32 v21, v27, v150
	v_bfe_u32 v23, v21, 16, 1
	v_add3_u32 v21, v21, v23, s73
	v_and_b32_e32 v23, 0xffff0000, v21
	v_add_u32_e32 v21, 2, v19
	v_and_b32_e32 v21, 0x7fa, v21
	v_lshlrev_b32_e32 v21, 2, v21
	ds_read2_b32 v[26:27], v20 offset0:66 offset1:99
	v_pk_add_f32 v[22:23], v[28:29], v[22:23]
	s_waitcnt lgkmcnt(0)
	v_mul_f32_e32 v28, v26, v138
	s_waitcnt vmcnt(0)
	v_mul_f32_e32 v21, v26, v152
	v_bfe_u32 v24, v21, 16, 1
	v_add3_u32 v21, v21, v24, s73
	v_and_b32_e32 v29, 0xffff0000, v21
	v_mul_f32_e32 v24, v27, v139
	v_pk_add_f32 v[22:23], v[22:23], v[28:29]
	s_waitcnt vmcnt(0)
	v_mul_f32_e32 v21, v27, v153
	v_bfe_u32 v25, v21, 16, 1
	v_add3_u32 v21, v21, v25, s73
	v_and_b32_e32 v25, 0xffff0000, v21
	v_pk_add_f32 v[22:23], v[22:23], v[24:25]
	ds_read2_b32 v[24:25], v20 offset0:132 offset1:165
	v_add_u32_e32 v21, 4, v19
	s_waitcnt lgkmcnt(0)
	v_mul_f32_e32 v26, v24, v144
	v_and_b32_e32 v0, 0x7fc, v21
	v_lshlrev_b32_e32 v0, 2, v0
	s_waitcnt vmcnt(0)
	v_mul_f32_e32 v0, v24, v158
	v_bfe_u32 v21, v0, 16, 1
	v_add3_u32 v0, v0, v21, s73
	v_and_b32_e32 v27, 0xffff0000, v0
	v_mul_f32_e32 v0, v25, v145
	v_pk_add_f32 v[22:23], v[22:23], v[26:27]
	s_waitcnt vmcnt(0)
	v_mul_f32_e32 v1, v25, v159
	v_bfe_u32 v21, v1, 16, 1
	v_add3_u32 v1, v1, v21, s73
	v_and_b32_e32 v1, 0xffff0000, v1
	v_pk_add_f32 v[0:1], v[22:23], v[0:1]
	ds_read2_b32 v[22:23], v20 offset0:198 offset1:231
	v_add_u32_e32 v21, 6, v19
	v_add_u32_e32 v20, 0x420, v20
	v_add_u32_e32 v19, 8, v19
	s_waitcnt lgkmcnt(0)
	v_mul_f32_e32 v24, v22, v146
	v_and_b32_e32 v2, 0x7fe, v21
	v_lshlrev_b32_e32 v2, 2, v2
	s_waitcnt vmcnt(0)
	v_mul_f32_e32 v2, v22, v164
	v_bfe_u32 v21, v2, 16, 1
	v_add3_u32 v2, v2, v21, s73
	v_and_b32_e32 v25, 0xffff0000, v2
	v_mul_f32_e32 v2, v23, v147
	v_pk_add_f32 v[0:1], v[0:1], v[24:25]
	s_waitcnt vmcnt(0)
	v_mul_f32_e32 v3, v23, v165
	v_bfe_u32 v8, v3, 16, 1
	v_add3_u32 v3, v3, v8, s73
	v_and_b32_e32 v3, 0xffff0000, v3
	v_pk_add_f32 v[8:9], v[0:1], v[2:3]
	s_cbranch_scc0 .LBB0_659
	v_mov_b32_e32 v0, v8
	v_mov_b32_e32 v1, v9
	s_nop 0
	v_permlane32_swap_b32_e32 v8, v0
	v_permlane32_swap_b32_e32 v9, v1
	v_cmp_gt_u32_e32 vcc, 32, v17
	s_and_saveexec_b64 s[12:13], vcc
	s_cbranch_execz .LBB0_662
	s_lshl_b64 s[48:49], s[56:57], 3
	s_add_u32 s70, s70, s48
	s_addc_u32 s71, s71, s49
	s_add_u32 s48, s40, s48
	v_add_f32_e32 v0, v8, v0
	s_addc_u32 s49, s41, s49
	s_lshl_b32 s74, s17, 3
	v_mul_f32_e32 v0, 0x4f800000, v0
	s_add_u32 s40, s70, s74
	v_rndne_f32_e32 v2, v0
	s_mov_b32 s70, 0x2f800000
	v_mul_f32_e64 v0, |v2|, s70
	s_addc_u32 s41, s71, 0
	v_floor_f32_e32 v0, v0
	s_mov_b32 s71, 0xcf800000
	v_add_f32_e32 v4, v9, v1
	v_fma_f32 v1, v0, s71, |v2|
	v_cvt_u32_f32_e32 v5, v1
	v_cvt_u32_f32_e32 v3, v0
	v_ashrrev_i32_e32 v6, 31, v2
	v_lshlrev_b32_e32 v184, 3, v18
	v_xor_b32_e32 v2, v5, v6
	v_xor_b32_e32 v3, v3, v6
	v_sub_co_u32_e32 v2, vcc, v2, v6
	v_lshl_add_u64 v[0:1], s[40:41], 0, v[184:185]
	s_nop 0
	v_subb_co_u32_e32 v3, vcc, v3, v6, vcc
	s_mov_b32 s40, 0x630000
	v_add_co_u32_e32 v0, vcc, s40, v0
	s_add_u32 s40, s48, s74
	s_nop 0
	v_addc_co_u32_e32 v1, vcc, 0, v1, vcc
	flat_atomic_add_x2 v[0:1], v[2:3]
	v_mul_f32_e32 v0, 0x4f800000, v4
	v_rndne_f32_e32 v2, v0
	v_mul_f32_e64 v0, |v2|, s70
	v_floor_f32_e32 v0, v0
	v_fma_f32 v1, v0, s71, |v2|
	v_cvt_u32_f32_e32 v4, v1
	v_cvt_u32_f32_e32 v3, v0
	v_ashrrev_i32_e32 v5, 31, v2
	s_addc_u32 s41, s49, 0
	v_xor_b32_e32 v2, v4, v5
	v_xor_b32_e32 v3, v3, v5
	v_sub_co_u32_e32 v2, vcc, v2, v5
	v_lshl_add_u64 v[0:1], s[40:41], 0, v[184:185]
	s_nop 0
	v_subb_co_u32_e32 v3, vcc, v3, v5, vcc
	v_add_co_u32_e32 v0, vcc, 0x62c000, v0
	s_nop 1
	v_addc_co_u32_e32 v1, vcc, 0, v1, vcc
	flat_atomic_add_x2 v[0:1], v[2:3]

; __device__ __forceinline__ float bf_round(float f) { return __uint_as_float(f2bf(f) << 16); }
; __device__ __forceinline__ void atomic_addq(i64* p, float v, float scale) { (void)__hip_atomic_fetch_add((unsigned long long*)p, (unsigned long long)(i64)__builtin_rintf(v * scale), __ATOMIC_RELAXED, __HIP_MEMORY_SCOPE_AGENT); }
; template <class Map>
; __device__ __forceinline__ void conv_item(const Frame& F, int it, const float* W, int K, int N, bf16_t* WT, const float* gk, int gmask, float gmul, const float* bk, i64* cs, i64* bw, Map map) {
;     ...
;             const int n = lane & 31, kh = lane >> 5; float sb = 0.f, sc = 0.f;
; #pragma unroll 8
;             for (int j = 0; j < 32; ++j) { const int kk = kh * 32 + j; const float w = scr[kk * 33 + n]; sb += bk[k0 + kk] * w; sc += bf_round(gk[(k0 + kk) & gmask] * gmul * w); }
;             { auto r = __builtin_amdgcn_permlane32_swap(__float_as_uint(sb), __float_as_uint(sb), false, false); sb = __uint_as_float(r[0]) + __uint_as_float(r[1]); }
;             { auto r = __builtin_amdgcn_permlane32_swap(__float_as_uint(sc), __float_as_uint(sc), false, false); sc = __uint_as_float(r[0]) + __uint_as_float(r[1]); }
;             if (lane < 32) { atomic_addq(bw + v0 + n, sb, FX_COL); atomic_addq(cs + v0 + n, sc, FX_COL); }
.LBB0_670:
	v_lshl_add_u64 v[132:133], v[4:5], 0, s[74:75]
	global_load_dword v134, v[132:133], off
	v_and_b32_e32 v135, 0x7f8, v20
	v_lshlrev_b32_e32 v135, 2, v135
	global_load_dword v136, v135, s[26:27]
	v_lshl_add_u64 v[138:139], v[6:7], 0, s[74:75]
	global_load_dwordx3 v[140:142], v[138:139], off offset:20
	v_lshl_add_u64 v[144:145], v[6:7], 0, s[74:75]
	global_load_dwordx4 v[148:151], v[144:145], off offset:4
	v_lshl_add_u64 v[146:147], v[8:9], 0, s[74:75]
	global_load_dword v137, v[146:147], off offset:4
	v_add_u32_e32 v143, 2, v20
	v_and_b32_e32 v152, 0x7fa, v143
	v_lshlrev_b32_e32 v152, 2, v152
	global_load_dword v153, v152, s[26:27]
	v_lshl_add_u64 v[154:155], v[8:9], 0, s[74:75]
	global_load_dword v156, v[154:155], off offset:12
	v_add_u32_e32 v157, 4, v20
	v_and_b32_e32 v158, 0x7fc, v157
	v_lshlrev_b32_e32 v158, 2, v158
	global_load_dword v159, v158, s[26:27]
	v_lshl_add_u64 v[160:161], v[8:9], 0, s[74:75]
	global_load_dword v162, v[160:161], off offset:20
	v_add_u32_e32 v163, 6, v20
	v_and_b32_e32 v164, 0x7fe, v163
	v_lshlrev_b32_e32 v164, 2, v164
	global_load_dword v165, v164, s[26:27]
	v_lshl_add_u64 v[166:167], v[8:9], 0, s[74:75]
	global_load_dword v168, v[166:167], off offset:28
	s_waitcnt vmcnt(0)
	v_lshl_add_u64 v[10:11], v[4:5], 0, s[74:75]
	ds_read2_b32 v[26:27], v21 offset1:33
	v_add_u32_e32 v30, 2, v20
	s_waitcnt vmcnt(0) lgkmcnt(0)
	v_mul_f32_e32 v10, v26, v134
	v_and_b32_e32 v2, 0x7f8, v20
	v_lshlrev_b32_e32 v2, 2, v2
	s_waitcnt vmcnt(0)
	v_mul_f32_e32 v2, v26, v136
	v_bfe_u32 v11, v2, 16, 1
	v_add3_u32 v2, v2, v11, s73
	v_and_b32_e32 v11, 0xffff0000, v2
	v_pk_add_f32 v[28:29], v[0:1], v[10:11]
	v_lshl_add_u64 v[10:11], v[6:7], 0, s[74:75]
	v_lshl_add_u64 v[10:11], v[8:9], 0, s[74:75]
	s_add_u32 s74, s74, 32
	s_addc_u32 s75, s75, 0
	s_cmpk_eq_i32 s74, 0x80
	s_waitcnt vmcnt(0)
	v_mul_f32_e32 v26, v27, v148
	s_waitcnt vmcnt(0)
	v_mul_f32_e32 v22, v27, v137
	v_bfe_u32 v27, v22, 16, 1
	v_add3_u32 v22, v22, v27, s73
	v_and_b32_e32 v27, 0xffff0000, v22
	v_pk_add_f32 v[26:27], v[28:29], v[26:27]
	ds_read2_b32 v[28:29], v21 offset0:66 offset1:99
	s_waitcnt lgkmcnt(0)
	v_mul_f32_e32 v22, v28, v149
	v_and_b32_e32 v23, 0x7fa, v30
	v_lshlrev_b32_e32 v23, 2, v23
	s_waitcnt vmcnt(0)
	v_mul_f32_e32 v23, v28, v153
	v_bfe_u32 v28, v23, 16, 1
	v_add3_u32 v23, v23, v28, s73
	v_and_b32_e32 v23, 0xffff0000, v23
	v_pk_add_f32 v[22:23], v[26:27], v[22:23]
	v_mul_f32_e32 v26, v29, v150
	v_add_u32_e32 v28, 4, v20
	s_waitcnt vmcnt(0)
	v_mul_f32_e32 v24, v29, v156
	v_bfe_u32 v27, v24, 16, 1
	v_add3_u32 v24, v24, v27, s73
	v_and_b32_e32 v27, 0xffff0000, v24
	v_pk_add_f32 v[22:23], v[22:23], v[26:27]
	ds_read2_b32 v[26:27], v21 offset0:132 offset1:165
	s_waitcnt lgkmcnt(0)
	v_mul_f32_e32 v24, v26, v151
	v_and_b32_e32 v25, 0x7fc, v28
	v_lshlrev_b32_e32 v25, 2, v25
	s_waitcnt vmcnt(0)
	v_mul_f32_e32 v25, v26, v159
	v_bfe_u32 v26, v25, 16, 1
	v_add3_u32 v25, v25, v26, s73
	v_and_b32_e32 v25, 0xffff0000, v25
	v_pk_add_f32 v[22:23], v[22:23], v[24:25]
	v_mul_f32_e32 v24, v27, v140
	v_add_u32_e32 v26, 6, v20
	v_add_u32_e32 v20, 8, v20
	s_waitcnt vmcnt(0)
	v_mul_f32_e32 v0, v27, v162
	v_bfe_u32 v25, v0, 16, 1
	v_add3_u32 v0, v0, v25, s73
	v_and_b32_e32 v25, 0xffff0000, v0
	v_pk_add_f32 v[22:23], v[22:23], v[24:25]
	ds_read2_b32 v[24:25], v21 offset0:198 offset1:231
	v_add_u32_e32 v21, 0x420, v21
	s_waitcnt lgkmcnt(0)
	v_mul_f32_e32 v0, v24, v141
	v_and_b32_e32 v1, 0x7fe, v26
	v_lshlrev_b32_e32 v1, 2, v1
	s_waitcnt vmcnt(0)
	v_mul_f32_e32 v1, v24, v165
	v_bfe_u32 v24, v1, 16, 1
	v_add3_u32 v1, v1, v24, s73
	v_and_b32_e32 v1, 0xffff0000, v1
	v_pk_add_f32 v[0:1], v[22:23], v[0:1]
	v_mul_f32_e32 v22, v25, v142
	s_waitcnt vmcnt(0)
	v_mul_f32_e32 v2, v25, v168
	v_bfe_u32 v10, v2, 16, 1
	v_add3_u32 v2, v2, v10, s73
	v_and_b32_e32 v23, 0xffff0000, v2
	v_pk_add_f32 v[0:1], v[0:1], v[22:23]
	s_cbranch_scc0 .LBB0_670
	v_mov_b32_e32 v2, v0
	v_mov_b32_e32 v4, v1
	s_nop 0
	v_permlane32_swap_b32_e32 v0, v2
	v_permlane32_swap_b32_e32 v1, v4
	v_cmp_gt_u32_e32 vcc, 32, v19
	s_and_saveexec_b64 s[16:17], vcc
	s_cbranch_execz .LBB0_673
	s_lshl_b64 s[74:75], s[56:57], 3
	s_add_u32 s87, s12, s74
	s_addc_u32 s90, s13, s75
	s_add_u32 s48, s48, s74
	v_add_f32_e32 v0, v0, v2
	s_addc_u32 s49, s49, s75
	s_ashr_i32 s71, s70, 31
	v_mul_f32_e32 v0, 0x4f800000, v0
	s_lshl_b64 s[12:13], s[70:71], 3
	v_rndne_f32_e32 v2, v0
	s_mov_b32 s71, 0x2f800000
	v_mul_f32_e64 v0, |v2|, s71
	v_floor_f32_e32 v0, v0
	s_mov_b32 s74, 0xcf800000
	v_add_f32_e32 v6, v1, v4
	v_fma_f32 v1, v0, s74, |v2|
	v_cvt_u32_f32_e32 v4, v0
	v_cvt_u32_f32_e32 v5, v1
	v_ashrrev_i32_e32 v2, 31, v2
	s_add_u32 s48, s48, s12
	v_xor_b32_e32 v7, v4, v2
	v_xor_b32_e32 v4, v5, v2
	s_addc_u32 s49, s49, s13
	v_lshlrev_b32_e32 v184, 3, v18
	v_sub_co_u32_e32 v4, vcc, v4, v2
	v_lshl_add_u64 v[0:1], s[48:49], 0, v[184:185]
	s_nop 0
	v_subb_co_u32_e32 v5, vcc, v7, v2, vcc
	s_mov_b32 s48, 0x616000
	v_add_co_u32_e32 v0, vcc, s48, v0
	s_add_u32 s12, s87, s12
	s_nop 0
	v_addc_co_u32_e32 v1, vcc, 0, v1, vcc
	flat_atomic_add_x2 v[0:1], v[4:5]
	v_mul_f32_e32 v0, 0x4f800000, v6
	v_rndne_f32_e32 v2, v0
	v_mul_f32_e64 v0, |v2|, s71
	v_floor_f32_e32 v0, v0
	v_fma_f32 v1, v0, s74, |v2|
	v_cvt_u32_f32_e32 v4, v0
	v_cvt_u32_f32_e32 v5, v1
	v_ashrrev_i32_e32 v2, 31, v2
	s_addc_u32 s13, s90, s13
	v_xor_b32_e32 v6, v4, v2
	v_xor_b32_e32 v4, v5, v2
	v_sub_co_u32_e32 v4, vcc, v4, v2
	v_lshl_add_u64 v[0:1], s[12:13], 0, v[184:185]
	s_nop 0
	v_subb_co_u32_e32 v5, vcc, v6, v2, vcc
	v_add_co_u32_e32 v0, vcc, 0x600000, v0
	s_nop 1
	v_addc_co_u32_e32 v1, vcc, 0, v1, vcc
	flat_atomic_add_x2 v[0:1], v[4:5]

; __device__ __forceinline__ float bf_round(float f) { return __uint_as_float(f2bf(f) << 16); }
; __device__ __forceinline__ void atomic_addq(i64* p, float v, float scale) { (void)__hip_atomic_fetch_add((unsigned long long*)p, (unsigned long long)(i64)__builtin_rintf(v * scale), __ATOMIC_RELAXED, __HIP_MEMORY_SCOPE_AGENT); }
; template <class Map>
; __device__ __forceinline__ void conv_item(const Frame& F, int it, const float* W, int K, int N, bf16_t* WT, const float* gk, int gmask, float gmul, const float* bk, i64* cs, i64* bw, Map map) {
;     ...
;             const int n = lane & 31, kh = lane >> 5; float sb = 0.f, sc = 0.f;
; #pragma unroll 8
;             for (int j = 0; j < 32; ++j) { const int kk = kh * 32 + j; const float w = scr[kk * 33 + n]; sb += bk[k0 + kk] * w; sc += bf_round(gk[(k0 + kk) & gmask] * gmul * w); }
;             { auto r = __builtin_amdgcn_permlane32_swap(__float_as_uint(sb), __float_as_uint(sb), false, false); sb = __uint_as_float(r[0]) + __uint_as_float(r[1]); }
;             { auto r = __builtin_amdgcn_permlane32_swap(__float_as_uint(sc), __float_as_uint(sc), false, false); sc = __uint_as_float(r[0]) + __uint_as_float(r[1]); }
;             if (lane < 32) { atomic_addq(bw + v0 + n, sb, FX_COL); atomic_addq(cs + v0 + n, sc, FX_COL); }
.LBB0_853:
	v_lshl_add_u64 v[132:133], v[6:7], 0, s[90:91]
	v_add_co_u32_e32 v132, vcc, 0x2000, v132
	v_addc_co_u32_e32 v133, vcc, 0, v133, vcc
	global_load_dwordx4 v[136:139], v[132:133], off
	v_lshl_add_u64 v[134:135], v[6:7], 0, s[90:91]
	v_lshl_add_u64 v[140:141], v[134:135], 0, s[78:79]
	global_load_dwordx4 v[144:147], v[140:141], off offset:16
	v_and_b32_e32 v142, 0x7f8, v17
	v_lshlrev_b32_e32 v142, 2, v142
	global_load_dword v143, v142, s[84:85]
	v_lshl_add_u64 v[148:149], v[4:5], 0, s[90:91]
	v_add_co_u32_e32 v148, vcc, s16, v148
	v_addc_co_u32_e32 v149, vcc, 0, v149, vcc
	global_load_dword v150, v[148:149], off offset:4
	v_add_u32_e32 v151, 2, v17
	v_and_b32_e32 v152, 0x7fa, v151
	v_lshlrev_b32_e32 v152, 2, v152
	global_load_dword v153, v152, s[84:85]
	v_lshl_add_u64 v[154:155], v[4:5], 0, s[90:91]
	v_add_co_u32_e32 v154, vcc, s16, v154
	v_addc_co_u32_e32 v155, vcc, 0, v155, vcc
	global_load_dword v156, v[154:155], off offset:12
	v_add_u32_e32 v157, 4, v17
	v_and_b32_e32 v158, 0x7fc, v157
	v_lshlrev_b32_e32 v158, 2, v158
	global_load_dword v159, v158, s[84:85]
	v_lshl_add_u64 v[160:161], v[4:5], 0, s[90:91]
	v_add_co_u32_e32 v160, vcc, s16, v160
	v_addc_co_u32_e32 v161, vcc, 0, v161, vcc
	global_load_dword v162, v[160:161], off offset:20
	v_add_u32_e32 v163, 6, v17
	v_and_b32_e32 v164, 0x7fe, v163
	v_lshlrev_b32_e32 v164, 2, v164
	global_load_dword v165, v164, s[84:85]
	v_lshl_add_u64 v[166:167], v[4:5], 0, s[90:91]
	v_add_co_u32_e32 v166, vcc, s16, v166
	v_addc_co_u32_e32 v167, vcc, 0, v167, vcc
	global_load_dword v168, v[166:167], off offset:28
	s_waitcnt vmcnt(0)
	v_lshl_add_u64 v[0:1], v[6:7], 0, s[90:91]
	v_lshl_add_u64 v[2:3], v[0:1], 0, s[78:79]
	v_add_co_u32_e32 v0, vcc, 0x2000, v0
	ds_read2_b32 v[32:33], v27 offset1:33
	s_nop 0
	v_addc_co_u32_e32 v1, vcc, 0, v1, vcc
	s_nop 0
	s_waitcnt vmcnt(1) lgkmcnt(0)
	v_mul_f32_e32 v34, v32, v136
	v_and_b32_e32 v28, 0x7f8, v17
	v_lshlrev_b32_e32 v28, 2, v28
	s_waitcnt vmcnt(0)
	v_mul_f32_e32 v28, v32, v143
	v_bfe_u32 v32, v28, 16, 1
	v_add3_u32 v28, v28, v32, s73
	v_and_b32_e32 v35, 0xffff0000, v28
	v_pk_add_f32 v[34:35], v[8:9], v[34:35]
	v_lshl_add_u64 v[8:9], v[4:5], 0, s[90:91]
	v_add_co_u32_e32 v8, vcc, s16, v8
	v_mul_f32_e32 v28, v33, v137
	s_nop 0
	v_addc_co_u32_e32 v9, vcc, 0, v9, vcc
	s_add_u32 s90, s90, 32
	s_addc_u32 s91, s91, 0
	s_cmpk_eq_i32 s90, 0x80
	s_waitcnt vmcnt(0)
	v_mul_f32_e32 v29, v33, v150
	v_bfe_u32 v32, v29, 16, 1
	v_add3_u32 v29, v29, v32, s73
	ds_read2_b32 v[32:33], v27 offset0:66 offset1:99
	v_and_b32_e32 v29, 0xffff0000, v29
	v_pk_add_f32 v[28:29], v[34:35], v[28:29]
	v_add_u32_e32 v35, 2, v17
	s_waitcnt lgkmcnt(0)
	v_mul_f32_e32 v34, v32, v138
	v_and_b32_e32 v30, 0x7fa, v35
	v_lshlrev_b32_e32 v30, 2, v30
	s_waitcnt vmcnt(0)
	v_mul_f32_e32 v30, v32, v153
	v_bfe_u32 v32, v30, 16, 1
	v_add3_u32 v30, v30, v32, s73
	v_and_b32_e32 v35, 0xffff0000, v30
	v_mul_f32_e32 v30, v33, v139
	v_pk_add_f32 v[28:29], v[28:29], v[34:35]
	s_waitcnt vmcnt(0)
	v_mul_f32_e32 v31, v33, v156
	v_bfe_u32 v32, v31, 16, 1
	v_add3_u32 v31, v31, v32, s73
	v_and_b32_e32 v31, 0xffff0000, v31
	v_pk_add_f32 v[28:29], v[28:29], v[30:31]
	ds_read2_b32 v[30:31], v27 offset0:132 offset1:165
	v_add_u32_e32 v33, 4, v17
	s_waitcnt lgkmcnt(0)
	v_mul_f32_e32 v32, v30, v144
	v_and_b32_e32 v0, 0x7fc, v33
	v_lshlrev_b32_e32 v0, 2, v0
	s_waitcnt vmcnt(0)
	v_mul_f32_e32 v0, v30, v159
	v_bfe_u32 v30, v0, 16, 1
	v_add3_u32 v0, v0, v30, s73
	v_and_b32_e32 v33, 0xffff0000, v0
	v_mul_f32_e32 v0, v31, v145
	v_pk_add_f32 v[28:29], v[28:29], v[32:33]
	s_waitcnt vmcnt(0)
	v_mul_f32_e32 v1, v31, v162
	v_bfe_u32 v30, v1, 16, 1
	v_add3_u32 v1, v1, v30, s73
	v_and_b32_e32 v1, 0xffff0000, v1
	v_pk_add_f32 v[0:1], v[28:29], v[0:1]
	ds_read2_b32 v[28:29], v27 offset0:198 offset1:231
	v_add_u32_e32 v31, 6, v17
	v_add_u32_e32 v27, 0x420, v27
	v_add_u32_e32 v17, 8, v17
	s_waitcnt lgkmcnt(0)
	v_mul_f32_e32 v30, v28, v146
	v_and_b32_e32 v2, 0x7fe, v31
	v_lshlrev_b32_e32 v2, 2, v2
	s_waitcnt vmcnt(0)
	v_mul_f32_e32 v2, v28, v165
	v_bfe_u32 v28, v2, 16, 1
	v_add3_u32 v2, v2, v28, s73
	v_and_b32_e32 v31, 0xffff0000, v2
	v_mul_f32_e32 v2, v29, v147
	v_pk_add_f32 v[0:1], v[0:1], v[30:31]
	s_waitcnt vmcnt(0)
	v_mul_f32_e32 v3, v29, v168
	v_bfe_u32 v8, v3, 16, 1
	v_add3_u32 v3, v3, v8, s73
	v_and_b32_e32 v3, 0xffff0000, v3
	v_pk_add_f32 v[8:9], v[0:1], v[2:3]
	s_cbranch_scc0 .LBB0_853
	v_mov_b32_e32 v0, v8
	v_mov_b32_e32 v1, v9
	s_nop 0
	v_permlane32_swap_b32_e32 v8, v0
	v_permlane32_swap_b32_e32 v9, v1
	v_cmp_gt_u32_e32 vcc, 32, v15
	s_and_saveexec_b64 s[16:17], vcc
	s_cbranch_execz .LBB0_856
	v_add_f32_e32 v4, v8, v0
	s_lshl_b64 s[78:79], s[54:55], 3
	v_mul_f32_e32 v4, 0x4f800000, v4
	s_add_u32 s48, s48, s78
	v_rndne_f32_e32 v4, v4
	s_mov_b32 s21, 0x2f800000
	s_addc_u32 s49, s49, s79
	v_lshlrev_b32_e32 v184, 3, v12
	v_mul_f32_e64 v5, |v4|, s21
	v_add_f32_e32 v6, v9, v1
	v_lshl_add_u64 v[0:1], s[48:49], 0, v[184:185]
	v_floor_f32_e32 v5, v5
	s_mov_b32 s48, 0xcf800000
	v_fma_f32 v7, v5, s48, |v4|
	v_cvt_u32_f32_e32 v7, v7
	v_cvt_u32_f32_e32 v5, v5
	v_ashrrev_i32_e32 v8, 31, v4
	v_lshlrev_b32_e32 v2, 3, v16
	v_xor_b32_e32 v4, v7, v8
	v_mov_b32_e32 v3, v185
	v_xor_b32_e32 v5, v5, v8
	v_sub_co_u32_e32 v4, vcc, v4, v8
	v_lshl_add_u64 v[0:1], v[0:1], 0, v[2:3]
	s_nop 0
	v_subb_co_u32_e32 v5, vcc, v5, v8, vcc
	s_mov_b32 s49, 0x630000
	s_add_u32 s12, s12, s78
	v_add_co_u32_e32 v0, vcc, s49, v0
	s_addc_u32 s13, s13, s79
	s_nop 0
	v_addc_co_u32_e32 v1, vcc, 0, v1, vcc
	flat_atomic_add_x2 v[0:1], v[4:5]
	v_lshl_add_u64 v[0:1], s[12:13], 0, v[184:185]
	v_lshl_add_u64 v[0:1], v[0:1], 0, v[2:3]
	v_mul_f32_e32 v2, 0x4f800000, v6
	v_rndne_f32_e32 v2, v2
	v_mul_f32_e64 v3, |v2|, s21
	v_floor_f32_e32 v3, v3
	v_fma_f32 v4, v3, s48, |v2|
	v_cvt_u32_f32_e32 v4, v4
	v_cvt_u32_f32_e32 v3, v3
	v_ashrrev_i32_e32 v5, 31, v2
	v_xor_b32_e32 v2, v4, v5
	v_xor_b32_e32 v3, v3, v5
	v_sub_co_u32_e32 v2, vcc, v2, v5
	s_nop 1
	v_subb_co_u32_e32 v3, vcc, v3, v5, vcc
	v_add_co_u32_e32 v0, vcc, 0x62c000, v0
	s_nop 1
	v_addc_co_u32_e32 v1, vcc, 0, v1, vcc
	flat_atomic_add_x2 v[0:1], v[2:3]

; __device__ __forceinline__ float bf_round(float f) { return __uint_as_float(f2bf(f) << 16); }
; __device__ __forceinline__ void atomic_addq(i64* p, float v, float scale) { (void)__hip_atomic_fetch_add((unsigned long long*)p, (unsigned long long)(i64)__builtin_rintf(v * scale), __ATOMIC_RELAXED, __HIP_MEMORY_SCOPE_AGENT); }
; template <class Map>
; __device__ __forceinline__ void conv_item(const Frame& F, int it, const float* W, int K, int N, bf16_t* WT, const float* gk, int gmask, float gmul, const float* bk, i64* cs, i64* bw, Map map) {
;     ...
;             const int n = lane & 31, kh = lane >> 5; float sb = 0.f, sc = 0.f;
; #pragma unroll 8
;             for (int j = 0; j < 32; ++j) { const int kk = kh * 32 + j; const float w = scr[kk * 33 + n]; sb += bk[k0 + kk] * w; sc += bf_round(gk[(k0 + kk) & gmask] * gmul * w); }
;             { auto r = __builtin_amdgcn_permlane32_swap(__float_as_uint(sb), __float_as_uint(sb), false, false); sb = __uint_as_float(r[0]) + __uint_as_float(r[1]); }
;             { auto r = __builtin_amdgcn_permlane32_swap(__float_as_uint(sc), __float_as_uint(sc), false, false); sc = __uint_as_float(r[0]) + __uint_as_float(r[1]); }
;             if (lane < 32) { atomic_addq(bw + v0 + n, sb, FX_COL); atomic_addq(cs + v0 + n, sc, FX_COL); }
.LBB0_864:
	v_lshl_add_u64 v[132:133], v[6:7], 0, s[12:13]
	global_load_dword v134, v[132:133], off
	v_and_b32_e32 v135, 0x7f8, v27
	v_lshlrev_b32_e32 v135, 2, v135
	global_load_dword v136, v135, s[84:85]
	v_lshl_add_u64 v[138:139], v[8:9], 0, s[12:13]
	global_load_dwordx3 v[140:142], v[138:139], off offset:20
	v_lshl_add_u64 v[144:145], v[8:9], 0, s[12:13]
	global_load_dwordx4 v[148:151], v[144:145], off offset:4
	v_lshl_add_u64 v[146:147], v[10:11], 0, s[12:13]
	global_load_dword v137, v[146:147], off offset:4
	v_add_u32_e32 v143, 2, v27
	v_and_b32_e32 v143, 0x7fa, v143
	v_lshlrev_b32_e32 v143, 2, v143
	global_load_dword v152, v143, s[84:85]
	v_lshl_add_u64 v[154:155], v[10:11], 0, s[12:13]
	global_load_dword v153, v[154:155], off offset:12
	v_add_u32_e32 v156, 4, v27
	v_and_b32_e32 v156, 0x7fc, v156
	v_lshlrev_b32_e32 v156, 2, v156
	global_load_dword v157, v156, s[84:85]
	v_lshl_add_u64 v[158:159], v[10:11], 0, s[12:13]
	global_load_dword v160, v[158:159], off offset:20
	v_add_u32_e32 v161, 6, v27
	v_and_b32_e32 v162, 0x7fe, v161
	v_lshlrev_b32_e32 v162, 2, v162
	global_load_dword v163, v162, s[84:85]
	v_lshl_add_u64 v[164:165], v[10:11], 0, s[12:13]
	global_load_dword v166, v[164:165], off offset:28
	s_waitcnt vmcnt(0)
	v_lshl_add_u64 v[12:13], v[6:7], 0, s[12:13]
	ds_read2_b32 v[34:35], v28 offset1:33
	s_waitcnt vmcnt(0) lgkmcnt(0)
	v_mul_f32_e32 v12, v34, v134
	v_and_b32_e32 v2, 0x7f8, v27
	v_lshlrev_b32_e32 v2, 2, v2
	s_waitcnt vmcnt(0)
	v_mul_f32_e32 v2, v34, v136
	v_bfe_u32 v13, v2, 16, 1
	v_add3_u32 v2, v2, v13, s73
	v_and_b32_e32 v13, 0xffff0000, v2
	v_pk_add_f32 v[36:37], v[0:1], v[12:13]
	v_lshl_add_u64 v[12:13], v[8:9], 0, s[12:13]
	v_lshl_add_u64 v[12:13], v[10:11], 0, s[12:13]
	s_add_u32 s12, s12, 32
	s_addc_u32 s13, s13, 0
	s_cmpk_eq_i32 s12, 0x80
	s_waitcnt vmcnt(1)
	v_mul_f32_e32 v34, v35, v148
	s_waitcnt vmcnt(0)
	v_mul_f32_e32 v29, v35, v137
	v_bfe_u32 v30, v29, 16, 1
	v_add3_u32 v29, v29, v30, s73
	v_and_b32_e32 v35, 0xffff0000, v29
	v_add_u32_e32 v29, 2, v27
	v_and_b32_e32 v29, 0x7fa, v29
	v_lshlrev_b32_e32 v29, 2, v29
	v_pk_add_f32 v[34:35], v[36:37], v[34:35]
	ds_read2_b32 v[36:37], v28 offset0:66 offset1:99
	s_waitcnt lgkmcnt(0)
	v_mul_f32_e32 v30, v36, v149
	s_waitcnt vmcnt(0)
	v_mul_f32_e32 v29, v36, v152
	v_bfe_u32 v31, v29, 16, 1
	v_add3_u32 v29, v29, v31, s73
	v_and_b32_e32 v31, 0xffff0000, v29
	v_pk_add_f32 v[30:31], v[34:35], v[30:31]
	v_mul_f32_e32 v34, v37, v150
	s_waitcnt vmcnt(0)
	v_mul_f32_e32 v29, v37, v153
	v_bfe_u32 v32, v29, 16, 1
	v_add3_u32 v29, v29, v32, s73
	v_and_b32_e32 v35, 0xffff0000, v29
	v_add_u32_e32 v29, 4, v27
	v_and_b32_e32 v29, 0x7fc, v29
	v_lshlrev_b32_e32 v29, 2, v29
	v_pk_add_f32 v[30:31], v[30:31], v[34:35]
	ds_read2_b32 v[34:35], v28 offset0:132 offset1:165
	s_waitcnt lgkmcnt(0)
	v_mul_f32_e32 v32, v34, v151
	s_waitcnt vmcnt(0)
	v_mul_f32_e32 v29, v34, v157
	v_bfe_u32 v33, v29, 16, 1
	v_add3_u32 v29, v29, v33, s73
	v_and_b32_e32 v33, 0xffff0000, v29
	v_pk_add_f32 v[30:31], v[30:31], v[32:33]
	v_mul_f32_e32 v32, v35, v140
	s_waitcnt vmcnt(0)
	v_mul_f32_e32 v0, v35, v160
	v_bfe_u32 v29, v0, 16, 1
	v_add3_u32 v0, v0, v29, s73
	v_and_b32_e32 v33, 0xffff0000, v0
	v_pk_add_f32 v[30:31], v[30:31], v[32:33]
	ds_read2_b32 v[32:33], v28 offset0:198 offset1:231
	v_add_u32_e32 v29, 6, v27
	v_add_u32_e32 v27, 8, v27
	v_add_u32_e32 v28, 0x420, v28
	s_waitcnt lgkmcnt(0)
	v_mul_f32_e32 v0, v32, v141
	v_and_b32_e32 v1, 0x7fe, v29
	v_lshlrev_b32_e32 v1, 2, v1
	s_waitcnt vmcnt(0)
	v_mul_f32_e32 v1, v32, v163
	v_bfe_u32 v29, v1, 16, 1
	v_add3_u32 v1, v1, v29, s73
	v_and_b32_e32 v1, 0xffff0000, v1
	v_pk_add_f32 v[0:1], v[30:31], v[0:1]
	v_mul_f32_e32 v30, v33, v142
	s_waitcnt vmcnt(0)
	v_mul_f32_e32 v2, v33, v166
	v_bfe_u32 v12, v2, 16, 1
	v_add3_u32 v2, v2, v12, s73
	v_and_b32_e32 v31, 0xffff0000, v2
	v_pk_add_f32 v[0:1], v[0:1], v[30:31]
	s_cbranch_scc0 .LBB0_864
	v_mov_b32_e32 v2, v0
	v_mov_b32_e32 v6, v1
	s_nop 0
	v_permlane32_swap_b32_e32 v0, v2
	v_permlane32_swap_b32_e32 v1, v6
	v_cmp_gt_u32_e32 vcc, 32, v5
	s_and_saveexec_b64 s[12:13], vcc
	s_cbranch_execz .LBB0_867
	s_lshl_b64 s[16:17], s[54:55], 3
	s_add_u32 s38, s48, s16
	s_addc_u32 s39, s49, s17
	s_add_u32 s16, s90, s16
	v_add_f32_e32 v2, v0, v2
	v_ashrrev_i32_e32 v5, 31, v4
	s_addc_u32 s17, s91, s17
	v_add_f32_e32 v10, v1, v6
	v_lshlrev_b64 v[0:1], 3, v[4:5]
	v_mul_f32_e32 v2, 0x4f800000, v2
	v_lshl_add_u64 v[6:7], s[16:17], 0, v[0:1]
	v_rndne_f32_e32 v2, v2
	s_mov_b32 s16, 0x2f800000
	v_mul_f32_e64 v5, |v2|, s16
	v_floor_f32_e32 v5, v5
	s_mov_b32 s17, 0xcf800000
	v_fma_f32 v8, v5, s17, |v2|
	v_cvt_u32_f32_e32 v8, v8
	v_cvt_u32_f32_e32 v5, v5
	v_ashrrev_i32_e32 v2, 31, v2
	v_lshlrev_b32_e32 v184, 3, v26
	v_xor_b32_e32 v8, v8, v2
	v_xor_b32_e32 v5, v5, v2
	v_sub_co_u32_e32 v8, vcc, v8, v2
	v_lshl_add_u64 v[6:7], v[6:7], 0, v[184:185]
	s_nop 0
	v_subb_co_u32_e32 v9, vcc, v5, v2, vcc
	v_mul_f32_e32 v2, 0x4f800000, v10
	s_mov_b32 s21, 0x616000
	v_rndne_f32_e32 v2, v2
	v_add_co_u32_e32 v6, vcc, s21, v6
	v_mul_f32_e64 v5, |v2|, s16
	s_nop 0
	v_addc_co_u32_e32 v7, vcc, 0, v7, vcc
	v_floor_f32_e32 v5, v5
	flat_atomic_add_x2 v[6:7], v[8:9]
	v_fma_f32 v6, v5, s17, |v2|
	v_cvt_u32_f32_e32 v6, v6
	v_cvt_u32_f32_e32 v5, v5
	v_ashrrev_i32_e32 v2, 31, v2
	v_lshl_add_u64 v[0:1], s[38:39], 0, v[0:1]
	v_xor_b32_e32 v6, v6, v2
	v_xor_b32_e32 v5, v5, v2
	v_sub_co_u32_e32 v6, vcc, v6, v2
	v_lshl_add_u64 v[0:1], v[0:1], 0, v[184:185]
	s_nop 0
	v_subb_co_u32_e32 v7, vcc, v5, v2, vcc
	v_add_co_u32_e32 v0, vcc, 0x600000, v0
	s_nop 1
	v_addc_co_u32_e32 v1, vcc, 0, v1, vcc
	flat_atomic_add_x2 v[0:1], v[6:7]

; __device__ __forceinline__ float bf_round(float f) { return __uint_as_float(f2bf(f) << 16); }
; __device__ __forceinline__ void atomic_addq(i64* p, float v, float scale) { (void)__hip_atomic_fetch_add((unsigned long long*)p, (unsigned long long)(i64)__builtin_rintf(v * scale), __ATOMIC_RELAXED, __HIP_MEMORY_SCOPE_AGENT); }
; template <class Map>
; __device__ __forceinline__ void conv_item(const Frame& F, int it, const float* W, int K, int N, bf16_t* WT, const float* gk, int gmask, float gmul, const float* bk, i64* cs, i64* bw, Map map) {
;     ...
;             const int n = lane & 31, kh = lane >> 5; float sb = 0.f, sc = 0.f;
; #pragma unroll 8
;             for (int j = 0; j < 32; ++j) { const int kk = kh * 32 + j; const float w = scr[kk * 33 + n]; sb += bk[k0 + kk] * w; sc += bf_round(gk[(k0 + kk) & gmask] * gmul * w); }
;             { auto r = __builtin_amdgcn_permlane32_swap(__float_as_uint(sb), __float_as_uint(sb), false, false); sb = __uint_as_float(r[0]) + __uint_as_float(r[1]); }
;             { auto r = __builtin_amdgcn_permlane32_swap(__float_as_uint(sc), __float_as_uint(sc), false, false); sc = __uint_as_float(r[0]) + __uint_as_float(r[1]); }
;             if (lane < 32) { atomic_addq(bw + v0 + n, sb, FX_COL); atomic_addq(cs + v0 + n, sc, FX_COL); }
.LBB0_1210:
	v_lshl_add_u64 v[132:133], v[6:7], 0, s[86:87]
	v_add_co_u32_e32 v132, vcc, 0x2000, v132
	v_addc_co_u32_e32 v133, vcc, 0, v133, vcc
	global_load_dwordx4 v[136:139], v[132:133], off
	v_lshl_add_u64 v[134:135], v[6:7], 0, s[86:87]
	v_lshl_add_u64 v[140:141], v[134:135], 0, s[56:57]
	global_load_dwordx4 v[144:147], v[140:141], off offset:16
	v_and_b32_e32 v142, 0x7f8, v27
	v_lshlrev_b32_e32 v142, 2, v142
	global_load_dword v143, v142, s[84:85]
	v_lshl_add_u64 v[148:149], v[4:5], 0, s[86:87]
	v_add_co_u32_e32 v148, vcc, s16, v148
	v_addc_co_u32_e32 v149, vcc, 0, v149, vcc
	global_load_dword v150, v[148:149], off offset:4
	v_add_u32_e32 v151, 2, v27
	v_and_b32_e32 v151, 0x7fa, v151
	v_lshlrev_b32_e32 v151, 2, v151
	global_load_dword v152, v151, s[84:85]
	v_lshl_add_u64 v[154:155], v[4:5], 0, s[86:87]
	v_add_co_u32_e32 v154, vcc, s16, v154
	v_addc_co_u32_e32 v155, vcc, 0, v155, vcc
	global_load_dword v153, v[154:155], off offset:12
	v_add_u32_e32 v156, 4, v27
	v_and_b32_e32 v157, 0x7fc, v156
	v_lshlrev_b32_e32 v157, 2, v157
	global_load_dword v158, v157, s[84:85]
	v_lshl_add_u64 v[160:161], v[4:5], 0, s[86:87]
	v_add_co_u32_e32 v160, vcc, s16, v160
	v_addc_co_u32_e32 v161, vcc, 0, v161, vcc
	global_load_dword v159, v[160:161], off offset:20
	v_add_u32_e32 v162, 6, v27
	v_and_b32_e32 v163, 0x7fe, v162
	v_lshlrev_b32_e32 v163, 2, v163
	global_load_dword v164, v163, s[84:85]
	v_lshl_add_u64 v[166:167], v[4:5], 0, s[86:87]
	v_add_co_u32_e32 v166, vcc, s16, v166
	v_addc_co_u32_e32 v167, vcc, 0, v167, vcc
	global_load_dword v165, v[166:167], off offset:28
	s_waitcnt vmcnt(0)
	v_lshl_add_u64 v[0:1], v[6:7], 0, s[86:87]
	v_lshl_add_u64 v[2:3], v[0:1], 0, s[56:57]
	v_add_co_u32_e32 v0, vcc, 0x2000, v0
	v_and_b32_e32 v29, 0x7f8, v27
	s_nop 0
	v_addc_co_u32_e32 v1, vcc, 0, v1, vcc
	v_lshlrev_b32_e32 v29, 2, v29
	ds_read2_b32 v[34:35], v28 offset1:33
	s_nop 0
	s_waitcnt vmcnt(1) lgkmcnt(0)
	v_mul_f32_e32 v36, v34, v136
	s_waitcnt vmcnt(0)
	v_mul_f32_e32 v29, v34, v143
	v_bfe_u32 v30, v29, 16, 1
	v_add3_u32 v29, v29, v30, s73
	v_and_b32_e32 v37, 0xffff0000, v29
	v_pk_add_f32 v[36:37], v[10:11], v[36:37]
	v_lshl_add_u64 v[10:11], v[4:5], 0, s[86:87]
	v_add_co_u32_e32 v10, vcc, s16, v10
	v_mul_f32_e32 v30, v35, v137
	s_nop 0
	v_addc_co_u32_e32 v11, vcc, 0, v11, vcc
	s_add_u32 s86, s86, 32
	s_addc_u32 s87, s87, 0
	s_cmpk_eq_i32 s86, 0x80
	s_waitcnt vmcnt(0)
	v_mul_f32_e32 v29, v35, v150
	v_bfe_u32 v31, v29, 16, 1
	v_add3_u32 v29, v29, v31, s73
	v_and_b32_e32 v31, 0xffff0000, v29
	v_add_u32_e32 v29, 2, v27
	v_and_b32_e32 v29, 0x7fa, v29
	v_lshlrev_b32_e32 v29, 2, v29
	ds_read2_b32 v[34:35], v28 offset0:66 offset1:99
	v_pk_add_f32 v[30:31], v[36:37], v[30:31]
	s_waitcnt lgkmcnt(0)
	v_mul_f32_e32 v36, v34, v138
	s_waitcnt vmcnt(0)
	v_mul_f32_e32 v29, v34, v152
	v_bfe_u32 v32, v29, 16, 1
	v_add3_u32 v29, v29, v32, s73
	v_and_b32_e32 v37, 0xffff0000, v29
	v_mul_f32_e32 v32, v35, v139
	v_pk_add_f32 v[30:31], v[30:31], v[36:37]
	s_waitcnt vmcnt(0)
	v_mul_f32_e32 v29, v35, v153
	v_bfe_u32 v33, v29, 16, 1
	v_add3_u32 v29, v29, v33, s73
	v_and_b32_e32 v33, 0xffff0000, v29
	v_pk_add_f32 v[30:31], v[30:31], v[32:33]
	ds_read2_b32 v[32:33], v28 offset0:132 offset1:165
	v_add_u32_e32 v29, 4, v27
	s_waitcnt lgkmcnt(0)
	v_mul_f32_e32 v34, v32, v144
	v_and_b32_e32 v0, 0x7fc, v29
	v_lshlrev_b32_e32 v0, 2, v0
	s_waitcnt vmcnt(0)
	v_mul_f32_e32 v0, v32, v158
	v_bfe_u32 v29, v0, 16, 1
	v_add3_u32 v0, v0, v29, s73
	v_and_b32_e32 v35, 0xffff0000, v0
	v_mul_f32_e32 v0, v33, v145
	v_pk_add_f32 v[30:31], v[30:31], v[34:35]
	s_waitcnt vmcnt(0)
	v_mul_f32_e32 v1, v33, v159
	v_bfe_u32 v29, v1, 16, 1
	v_add3_u32 v1, v1, v29, s73
	v_and_b32_e32 v1, 0xffff0000, v1
	v_pk_add_f32 v[0:1], v[30:31], v[0:1]
	ds_read2_b32 v[30:31], v28 offset0:198 offset1:231
	v_add_u32_e32 v29, 6, v27
	v_add_u32_e32 v28, 0x420, v28
	v_add_u32_e32 v27, 8, v27
	s_waitcnt lgkmcnt(0)
	v_mul_f32_e32 v32, v30, v146
	v_and_b32_e32 v2, 0x7fe, v29
	v_lshlrev_b32_e32 v2, 2, v2
	s_waitcnt vmcnt(0)
	v_mul_f32_e32 v2, v30, v164
	v_bfe_u32 v29, v2, 16, 1
	v_add3_u32 v2, v2, v29, s73
	v_and_b32_e32 v33, 0xffff0000, v2
	v_mul_f32_e32 v2, v31, v147
	v_pk_add_f32 v[0:1], v[0:1], v[32:33]
	s_waitcnt vmcnt(0)
	v_mul_f32_e32 v3, v31, v165
	v_bfe_u32 v10, v3, 16, 1
	v_add3_u32 v3, v3, v10, s73
	v_and_b32_e32 v3, 0xffff0000, v3
	v_pk_add_f32 v[10:11], v[0:1], v[2:3]
	s_cbranch_scc0 .LBB0_1210
	v_mov_b32_e32 v0, v10
	v_mov_b32_e32 v1, v11
	s_nop 0
	v_permlane32_swap_b32_e32 v10, v0
	v_permlane32_swap_b32_e32 v11, v1
	v_cmp_gt_u32_e32 vcc, 32, v25
	s_and_saveexec_b64 s[16:17], vcc
	s_cbranch_execz .LBB0_1213
	v_readlane_b32 s56, v255, 58
	v_readlane_b32 s57, v255, 59
	s_lshl_b64 s[78:79], s[56:57], 3
	s_add_u32 s48, s48, s78
	v_add_f32_e32 v4, v10, v0
	s_addc_u32 s49, s49, s79
	v_lshlrev_b32_e32 v184, 3, v8
	v_mul_f32_e32 v4, 0x4f800000, v4
	v_add_f32_e32 v6, v11, v1
	v_lshl_add_u64 v[0:1], s[48:49], 0, v[184:185]
	v_rndne_f32_e32 v4, v4
	s_mov_b32 s48, 0x2f800000
	v_mul_f32_e64 v5, |v4|, s48
	v_floor_f32_e32 v5, v5
	s_mov_b32 s49, 0xcf800000
	v_fma_f32 v7, v5, s49, |v4|
	v_cvt_u32_f32_e32 v7, v7
	v_cvt_u32_f32_e32 v5, v5
	v_ashrrev_i32_e32 v10, 31, v4
	v_lshlrev_b32_e32 v2, 3, v26
	v_xor_b32_e32 v4, v7, v10
	v_mov_b32_e32 v3, v185
	v_xor_b32_e32 v5, v5, v10
	v_sub_co_u32_e32 v4, vcc, v4, v10
	v_lshl_add_u64 v[0:1], v[0:1], 0, v[2:3]
	s_nop 0
	v_subb_co_u32_e32 v5, vcc, v5, v10, vcc
	s_mov_b32 s56, 0x630000
	s_add_u32 s12, s12, s78
	v_add_co_u32_e32 v0, vcc, s56, v0
	s_addc_u32 s13, s13, s79
	s_nop 0
	v_addc_co_u32_e32 v1, vcc, 0, v1, vcc
	flat_atomic_add_x2 v[0:1], v[4:5]
	v_lshl_add_u64 v[0:1], s[12:13], 0, v[184:185]
	v_lshl_add_u64 v[0:1], v[0:1], 0, v[2:3]
	v_mul_f32_e32 v2, 0x4f800000, v6
	v_rndne_f32_e32 v2, v2
	v_mul_f32_e64 v3, |v2|, s48
	v_floor_f32_e32 v3, v3
	v_fma_f32 v4, v3, s49, |v2|
	v_cvt_u32_f32_e32 v4, v4
	v_cvt_u32_f32_e32 v3, v3
	v_ashrrev_i32_e32 v5, 31, v2
	v_xor_b32_e32 v2, v4, v5
	v_xor_b32_e32 v3, v3, v5
	v_sub_co_u32_e32 v2, vcc, v2, v5
	s_nop 1
	v_subb_co_u32_e32 v3, vcc, v3, v5, vcc
	v_add_co_u32_e32 v0, vcc, 0x62c000, v0
	s_nop 1
	v_addc_co_u32_e32 v1, vcc, 0, v1, vcc
	flat_atomic_add_x2 v[0:1], v[2:3]

; __device__ __forceinline__ float bf_round(float f) { return __uint_as_float(f2bf(f) << 16); }
; __device__ __forceinline__ void atomic_addq(i64* p, float v, float scale) { (void)__hip_atomic_fetch_add((unsigned long long*)p, (unsigned long long)(i64)__builtin_rintf(v * scale), __ATOMIC_RELAXED, __HIP_MEMORY_SCOPE_AGENT); }
; template <class Map>
; __device__ __forceinline__ void conv_item(const Frame& F, int it, const float* W, int K, int N, bf16_t* WT, const float* gk, int gmask, float gmul, const float* bk, i64* cs, i64* bw, Map map) {
;     ...
;             const int n = lane & 31, kh = lane >> 5; float sb = 0.f, sc = 0.f;
; #pragma unroll 8
;             for (int j = 0; j < 32; ++j) { const int kk = kh * 32 + j; const float w = scr[kk * 33 + n]; sb += bk[k0 + kk] * w; sc += bf_round(gk[(k0 + kk) & gmask] * gmul * w); }
;             { auto r = __builtin_amdgcn_permlane32_swap(__float_as_uint(sb), __float_as_uint(sb), false, false); sb = __uint_as_float(r[0]) + __uint_as_float(r[1]); }
;             { auto r = __builtin_amdgcn_permlane32_swap(__float_as_uint(sc), __float_as_uint(sc), false, false); sc = __uint_as_float(r[0]) + __uint_as_float(r[1]); }
;             if (lane < 32) { atomic_addq(bw + v0 + n, sb, FX_COL); atomic_addq(cs + v0 + n, sc, FX_COL); }
.LBB0_1221:
	v_lshl_add_u64 v[132:133], v[6:7], 0, s[12:13]
	global_load_dword v134, v[132:133], off
	v_and_b32_e32 v135, 0x7f8, v28
	v_lshlrev_b32_e32 v135, 2, v135
	global_load_dword v136, v135, s[70:71]
	v_lshl_add_u64 v[138:139], v[8:9], 0, s[12:13]
	global_load_dwordx3 v[140:142], v[138:139], off offset:20
	v_lshl_add_u64 v[144:145], v[8:9], 0, s[12:13]
	global_load_dwordx4 v[148:151], v[144:145], off offset:4
	v_lshl_add_u64 v[146:147], v[10:11], 0, s[12:13]
	global_load_dword v137, v[146:147], off offset:4
	v_add_u32_e32 v143, 2, v28
	v_and_b32_e32 v152, 0x7fa, v143
	v_lshlrev_b32_e32 v152, 2, v152
	global_load_dword v153, v152, s[70:71]
	v_lshl_add_u64 v[154:155], v[10:11], 0, s[12:13]
	global_load_dword v156, v[154:155], off offset:12
	v_add_u32_e32 v157, 4, v28
	v_and_b32_e32 v158, 0x7fc, v157
	v_lshlrev_b32_e32 v158, 2, v158
	global_load_dword v159, v158, s[70:71]
	v_lshl_add_u64 v[160:161], v[10:11], 0, s[12:13]
	global_load_dword v162, v[160:161], off offset:20
	v_add_u32_e32 v163, 6, v28
	v_and_b32_e32 v164, 0x7fe, v163
	v_lshlrev_b32_e32 v164, 2, v164
	global_load_dword v165, v164, s[70:71]
	v_lshl_add_u64 v[166:167], v[10:11], 0, s[12:13]
	global_load_dword v168, v[166:167], off offset:28
	s_waitcnt vmcnt(0)
	v_lshl_add_u64 v[12:13], v[6:7], 0, s[12:13]
	ds_read2_b32 v[34:35], v29 offset1:33
	v_add_u32_e32 v38, 2, v28
	s_waitcnt vmcnt(0) lgkmcnt(0)
	v_mul_f32_e32 v12, v34, v134
	v_and_b32_e32 v2, 0x7f8, v28
	v_lshlrev_b32_e32 v2, 2, v2
	s_waitcnt vmcnt(0)
	v_mul_f32_e32 v2, v34, v136
	v_bfe_u32 v13, v2, 16, 1
	v_add3_u32 v2, v2, v13, s73
	v_and_b32_e32 v13, 0xffff0000, v2
	v_pk_add_f32 v[36:37], v[0:1], v[12:13]
	v_lshl_add_u64 v[12:13], v[8:9], 0, s[12:13]
	v_lshl_add_u64 v[12:13], v[10:11], 0, s[12:13]
	s_add_u32 s12, s12, 32
	s_addc_u32 s13, s13, 0
	s_cmpk_eq_i32 s12, 0x80
	s_waitcnt vmcnt(0)
	v_mul_f32_e32 v34, v35, v148
	s_waitcnt vmcnt(0)
	v_mul_f32_e32 v30, v35, v137
	v_bfe_u32 v35, v30, 16, 1
	v_add3_u32 v30, v30, v35, s73
	v_and_b32_e32 v35, 0xffff0000, v30
	v_pk_add_f32 v[34:35], v[36:37], v[34:35]
	ds_read2_b32 v[36:37], v29 offset0:66 offset1:99
	s_waitcnt lgkmcnt(0)
	v_mul_f32_e32 v30, v36, v149
	v_and_b32_e32 v31, 0x7fa, v38
	v_lshlrev_b32_e32 v31, 2, v31
	s_waitcnt vmcnt(0)
	v_mul_f32_e32 v31, v36, v153
	v_bfe_u32 v36, v31, 16, 1
	v_add3_u32 v31, v31, v36, s73
	v_and_b32_e32 v31, 0xffff0000, v31
	v_pk_add_f32 v[30:31], v[34:35], v[30:31]
	v_mul_f32_e32 v34, v37, v150
	v_add_u32_e32 v36, 4, v28
	s_waitcnt vmcnt(0)
	v_mul_f32_e32 v32, v37, v156
	v_bfe_u32 v35, v32, 16, 1
	v_add3_u32 v32, v32, v35, s73
	v_and_b32_e32 v35, 0xffff0000, v32
	v_pk_add_f32 v[30:31], v[30:31], v[34:35]
	ds_read2_b32 v[34:35], v29 offset0:132 offset1:165
	s_waitcnt lgkmcnt(0)
	v_mul_f32_e32 v32, v34, v151
	v_and_b32_e32 v33, 0x7fc, v36
	v_lshlrev_b32_e32 v33, 2, v33
	s_waitcnt vmcnt(0)
	v_mul_f32_e32 v33, v34, v159
	v_bfe_u32 v34, v33, 16, 1
	v_add3_u32 v33, v33, v34, s73
	v_and_b32_e32 v33, 0xffff0000, v33
	v_pk_add_f32 v[30:31], v[30:31], v[32:33]
	v_mul_f32_e32 v32, v35, v140
	v_add_u32_e32 v34, 6, v28
	v_add_u32_e32 v28, 8, v28
	s_waitcnt vmcnt(0)
	v_mul_f32_e32 v0, v35, v162
	v_bfe_u32 v33, v0, 16, 1
	v_add3_u32 v0, v0, v33, s73
	v_and_b32_e32 v33, 0xffff0000, v0
	v_pk_add_f32 v[30:31], v[30:31], v[32:33]
	ds_read2_b32 v[32:33], v29 offset0:198 offset1:231
	v_add_u32_e32 v29, 0x420, v29
	s_waitcnt lgkmcnt(0)
	v_mul_f32_e32 v0, v32, v141
	v_and_b32_e32 v1, 0x7fe, v34
	v_lshlrev_b32_e32 v1, 2, v1
	s_waitcnt vmcnt(0)
	v_mul_f32_e32 v1, v32, v165
	v_bfe_u32 v32, v1, 16, 1
	v_add3_u32 v1, v1, v32, s73
	v_and_b32_e32 v1, 0xffff0000, v1
	v_pk_add_f32 v[0:1], v[30:31], v[0:1]
	v_mul_f32_e32 v30, v33, v142
	s_waitcnt vmcnt(0)
	v_mul_f32_e32 v2, v33, v168
	v_bfe_u32 v12, v2, 16, 1
	v_add3_u32 v2, v2, v12, s73
	v_and_b32_e32 v31, 0xffff0000, v2
	v_pk_add_f32 v[0:1], v[0:1], v[30:31]
	s_cbranch_scc0 .LBB0_1221
	v_mov_b32_e32 v2, v0
	v_mov_b32_e32 v6, v1
	s_nop 0
	v_permlane32_swap_b32_e32 v0, v2
	v_permlane32_swap_b32_e32 v1, v6
	v_cmp_gt_u32_e32 vcc, 32, v5
	s_and_saveexec_b64 s[12:13], vcc
	s_cbranch_execz .LBB0_1224
	v_readlane_b32 s16, v255, 58
	v_readlane_b32 s17, v255, 59
	s_lshl_b64 s[16:17], s[16:17], 3
	s_add_u32 s42, s48, s16
	s_addc_u32 s43, s49, s17
	s_add_u32 s16, s86, s16
	v_add_f32_e32 v2, v0, v2
	v_ashrrev_i32_e32 v5, 31, v4
	s_addc_u32 s17, s87, s17
	v_add_f32_e32 v10, v1, v6
	v_lshlrev_b64 v[0:1], 3, v[4:5]
	v_mul_f32_e32 v2, 0x4f800000, v2
	v_lshl_add_u64 v[6:7], s[16:17], 0, v[0:1]
	v_rndne_f32_e32 v2, v2
	s_mov_b32 s16, 0x2f800000
	v_mul_f32_e64 v5, |v2|, s16
	v_floor_f32_e32 v5, v5
	s_mov_b32 s17, 0xcf800000
	v_fma_f32 v8, v5, s17, |v2|
	v_cvt_u32_f32_e32 v8, v8
	v_cvt_u32_f32_e32 v5, v5
	v_ashrrev_i32_e32 v2, 31, v2
	v_lshlrev_b32_e32 v184, 3, v27
	v_xor_b32_e32 v8, v8, v2
	v_xor_b32_e32 v5, v5, v2
	v_sub_co_u32_e32 v8, vcc, v8, v2
	v_lshl_add_u64 v[6:7], v[6:7], 0, v[184:185]
	s_nop 0
	v_subb_co_u32_e32 v9, vcc, v5, v2, vcc
	v_mul_f32_e32 v2, 0x4f800000, v10
	s_mov_b32 s48, 0x616000
	v_rndne_f32_e32 v2, v2
	v_add_co_u32_e32 v6, vcc, s48, v6
	v_mul_f32_e64 v5, |v2|, s16
	s_nop 0
	v_addc_co_u32_e32 v7, vcc, 0, v7, vcc
	v_floor_f32_e32 v5, v5
	flat_atomic_add_x2 v[6:7], v[8:9]
	v_fma_f32 v6, v5, s17, |v2|
	v_cvt_u32_f32_e32 v6, v6
	v_cvt_u32_f32_e32 v5, v5
	v_ashrrev_i32_e32 v2, 31, v2
	v_lshl_add_u64 v[0:1], s[42:43], 0, v[0:1]
	v_xor_b32_e32 v6, v6, v2
	v_xor_b32_e32 v5, v5, v2
	v_sub_co_u32_e32 v6, vcc, v6, v2
	v_lshl_add_u64 v[0:1], v[0:1], 0, v[184:185]
	s_nop 0
	v_subb_co_u32_e32 v7, vcc, v5, v2, vcc
	v_add_co_u32_e32 v0, vcc, 0x600000, v0
	s_nop 1
	v_addc_co_u32_e32 v1, vcc, 0, v1, vcc
	flat_atomic_add_x2 v[0:1], v[6:7]

; __device__ __forceinline__ float bf_round(float f) { return __uint_as_float(f2bf(f) << 16); }
; __device__ __forceinline__ void atomic_addq(i64* p, float v, float scale) { (void)__hip_atomic_fetch_add((unsigned long long*)p, (unsigned long long)(i64)__builtin_rintf(v * scale), __ATOMIC_RELAXED, __HIP_MEMORY_SCOPE_AGENT); }
; template <class Map>
; __device__ __forceinline__ void conv_item(const Frame& F, int it, const float* W, int K, int N, bf16_t* WT, const float* gk, int gmask, float gmul, const float* bk, i64* cs, i64* bw, Map map) {
;     ...
;             const int n = lane & 31, kh = lane >> 5; float sb = 0.f, sc = 0.f;
; #pragma unroll 8
;             for (int j = 0; j < 32; ++j) { const int kk = kh * 32 + j; const float w = scr[kk * 33 + n]; sb += bk[k0 + kk] * w; sc += bf_round(gk[(k0 + kk) & gmask] * gmul * w); }
;             { auto r = __builtin_amdgcn_permlane32_swap(__float_as_uint(sb), __float_as_uint(sb), false, false); sb = __uint_as_float(r[0]) + __uint_as_float(r[1]); }
;             { auto r = __builtin_amdgcn_permlane32_swap(__float_as_uint(sc), __float_as_uint(sc), false, false); sc = __uint_as_float(r[0]) + __uint_as_float(r[1]); }
;             if (lane < 32) { atomic_addq(bw + v0 + n, sb, FX_COL); atomic_addq(cs + v0 + n, sc, FX_COL); }
.LBB0_1432:
	v_lshl_add_u64 v[132:133], v[6:7], 0, s[96:97]
	v_add_co_u32_e32 v132, vcc, 0x2000, v132
	v_addc_co_u32_e32 v133, vcc, 0, v133, vcc
	global_load_dwordx4 v[136:139], v[132:133], off
	v_lshl_add_u64 v[134:135], v[6:7], 0, s[96:97]
	v_lshl_add_u64 v[140:141], v[134:135], 0, s[78:79]
	global_load_dwordx4 v[144:147], v[140:141], off offset:16
	v_and_b32_e32 v142, 0x7f8, v27
	v_lshlrev_b32_e32 v142, 2, v142
	global_load_dword v143, v142, s[86:87]
	v_lshl_add_u64 v[148:149], v[4:5], 0, s[96:97]
	v_add_co_u32_e32 v148, vcc, s16, v148
	v_addc_co_u32_e32 v149, vcc, 0, v149, vcc
	global_load_dword v150, v[148:149], off offset:4
	v_add_u32_e32 v151, 2, v27
	v_and_b32_e32 v151, 0x7fa, v151
	v_lshlrev_b32_e32 v151, 2, v151
	global_load_dword v152, v151, s[86:87]
	v_lshl_add_u64 v[154:155], v[4:5], 0, s[96:97]
	v_add_co_u32_e32 v154, vcc, s16, v154
	v_addc_co_u32_e32 v155, vcc, 0, v155, vcc
	global_load_dword v153, v[154:155], off offset:12
	v_add_u32_e32 v156, 4, v27
	v_and_b32_e32 v157, 0x7fc, v156
	v_lshlrev_b32_e32 v157, 2, v157
	global_load_dword v158, v157, s[86:87]
	v_lshl_add_u64 v[160:161], v[4:5], 0, s[96:97]
	v_add_co_u32_e32 v160, vcc, s16, v160
	v_addc_co_u32_e32 v161, vcc, 0, v161, vcc
	global_load_dword v159, v[160:161], off offset:20
	v_add_u32_e32 v162, 6, v27
	v_and_b32_e32 v163, 0x7fe, v162
	v_lshlrev_b32_e32 v163, 2, v163
	global_load_dword v164, v163, s[86:87]
	v_lshl_add_u64 v[166:167], v[4:5], 0, s[96:97]
	v_add_co_u32_e32 v166, vcc, s16, v166
	v_addc_co_u32_e32 v167, vcc, 0, v167, vcc
	global_load_dword v165, v[166:167], off offset:28
	s_waitcnt vmcnt(0)
	v_lshl_add_u64 v[0:1], v[6:7], 0, s[96:97]
	v_lshl_add_u64 v[2:3], v[0:1], 0, s[78:79]
	v_add_co_u32_e32 v0, vcc, 0x2000, v0
	v_and_b32_e32 v29, 0x7f8, v27
	s_nop 0
	v_addc_co_u32_e32 v1, vcc, 0, v1, vcc
	v_lshlrev_b32_e32 v29, 2, v29
	ds_read2_b32 v[34:35], v28 offset1:33
	s_nop 0
	s_waitcnt vmcnt(1) lgkmcnt(0)
	v_mul_f32_e32 v36, v34, v136
	s_waitcnt vmcnt(0)
	v_mul_f32_e32 v29, v34, v143
	v_bfe_u32 v30, v29, 16, 1
	v_add3_u32 v29, v29, v30, s73
	v_and_b32_e32 v37, 0xffff0000, v29
	v_pk_add_f32 v[36:37], v[10:11], v[36:37]
	v_lshl_add_u64 v[10:11], v[4:5], 0, s[96:97]
	v_add_co_u32_e32 v10, vcc, s16, v10
	v_mul_f32_e32 v30, v35, v137
	s_nop 0
	v_addc_co_u32_e32 v11, vcc, 0, v11, vcc
	s_add_u32 s96, s96, 32
	s_addc_u32 s97, s97, 0
	s_cmpk_eq_i32 s96, 0x80
	s_waitcnt vmcnt(0)
	v_mul_f32_e32 v29, v35, v150
	v_bfe_u32 v31, v29, 16, 1
	v_add3_u32 v29, v29, v31, s73
	v_and_b32_e32 v31, 0xffff0000, v29
	v_add_u32_e32 v29, 2, v27
	v_and_b32_e32 v29, 0x7fa, v29
	v_lshlrev_b32_e32 v29, 2, v29
	ds_read2_b32 v[34:35], v28 offset0:66 offset1:99
	v_pk_add_f32 v[30:31], v[36:37], v[30:31]
	s_waitcnt lgkmcnt(0)
	v_mul_f32_e32 v36, v34, v138
	s_waitcnt vmcnt(0)
	v_mul_f32_e32 v29, v34, v152
	v_bfe_u32 v32, v29, 16, 1
	v_add3_u32 v29, v29, v32, s73
	v_and_b32_e32 v37, 0xffff0000, v29
	v_mul_f32_e32 v32, v35, v139
	v_pk_add_f32 v[30:31], v[30:31], v[36:37]
	s_waitcnt vmcnt(0)
	v_mul_f32_e32 v29, v35, v153
	v_bfe_u32 v33, v29, 16, 1
	v_add3_u32 v29, v29, v33, s73
	v_and_b32_e32 v33, 0xffff0000, v29
	v_pk_add_f32 v[30:31], v[30:31], v[32:33]
	ds_read2_b32 v[32:33], v28 offset0:132 offset1:165
	v_add_u32_e32 v29, 4, v27
	s_waitcnt lgkmcnt(0)
	v_mul_f32_e32 v34, v32, v144
	v_and_b32_e32 v0, 0x7fc, v29
	v_lshlrev_b32_e32 v0, 2, v0
	s_waitcnt vmcnt(0)
	v_mul_f32_e32 v0, v32, v158
	v_bfe_u32 v29, v0, 16, 1
	v_add3_u32 v0, v0, v29, s73
	v_and_b32_e32 v35, 0xffff0000, v0
	v_mul_f32_e32 v0, v33, v145
	v_pk_add_f32 v[30:31], v[30:31], v[34:35]
	s_waitcnt vmcnt(0)
	v_mul_f32_e32 v1, v33, v159
	v_bfe_u32 v29, v1, 16, 1
	v_add3_u32 v1, v1, v29, s73
	v_and_b32_e32 v1, 0xffff0000, v1
	v_pk_add_f32 v[0:1], v[30:31], v[0:1]
	ds_read2_b32 v[30:31], v28 offset0:198 offset1:231
	v_add_u32_e32 v29, 6, v27
	v_add_u32_e32 v28, 0x420, v28
	v_add_u32_e32 v27, 8, v27
	s_waitcnt lgkmcnt(0)
	v_mul_f32_e32 v32, v30, v146
	v_and_b32_e32 v2, 0x7fe, v29
	v_lshlrev_b32_e32 v2, 2, v2
	s_waitcnt vmcnt(0)
	v_mul_f32_e32 v2, v30, v164
	v_bfe_u32 v29, v2, 16, 1
	v_add3_u32 v2, v2, v29, s73
	v_and_b32_e32 v33, 0xffff0000, v2
	v_mul_f32_e32 v2, v31, v147
	v_pk_add_f32 v[0:1], v[0:1], v[32:33]
	s_waitcnt vmcnt(0)
	v_mul_f32_e32 v3, v31, v165
	v_bfe_u32 v10, v3, 16, 1
	v_add3_u32 v3, v3, v10, s73
	v_and_b32_e32 v3, 0xffff0000, v3
	v_pk_add_f32 v[10:11], v[0:1], v[2:3]
	s_cbranch_scc0 .LBB0_1432
	v_mov_b32_e32 v0, v10
	v_mov_b32_e32 v1, v11
	s_nop 0
	v_permlane32_swap_b32_e32 v10, v0
	v_permlane32_swap_b32_e32 v11, v1
	v_cmp_gt_u32_e32 vcc, 32, v25
	s_and_saveexec_b64 s[16:17], vcc
	s_cbranch_execz .LBB0_1435
	v_readlane_b32 s78, v255, 60
	v_readlane_b32 s79, v255, 61
	s_lshl_b64 s[78:79], s[78:79], 3
	s_add_u32 s48, s48, s78
	v_add_f32_e32 v4, v10, v0
	s_addc_u32 s49, s49, s79
	v_lshlrev_b32_e32 v184, 3, v8
	v_mul_f32_e32 v4, 0x4f800000, v4
	v_add_f32_e32 v6, v11, v1
	v_lshl_add_u64 v[0:1], s[48:49], 0, v[184:185]
	v_rndne_f32_e32 v4, v4
	s_mov_b32 s48, 0x2f800000
	v_mul_f32_e64 v5, |v4|, s48
	v_floor_f32_e32 v5, v5
	s_mov_b32 s49, 0xcf800000
	v_fma_f32 v7, v5, s49, |v4|
	v_cvt_u32_f32_e32 v7, v7
	v_cvt_u32_f32_e32 v5, v5
	v_ashrrev_i32_e32 v10, 31, v4
	v_lshlrev_b32_e32 v2, 3, v26
	v_xor_b32_e32 v4, v7, v10
	v_mov_b32_e32 v3, v185
	v_xor_b32_e32 v5, v5, v10
	v_sub_co_u32_e32 v4, vcc, v4, v10
	s_add_u32 s12, s12, s78
	v_lshl_add_u64 v[0:1], v[0:1], 0, v[2:3]
	v_subb_co_u32_e32 v5, vcc, v5, v10, vcc
	s_mov_b32 s78, 0x630000
	v_add_co_u32_e32 v0, vcc, s78, v0
	s_addc_u32 s13, s13, s79
	s_nop 0
	v_addc_co_u32_e32 v1, vcc, 0, v1, vcc
	flat_atomic_add_x2 v[0:1], v[4:5]
	v_lshl_add_u64 v[0:1], s[12:13], 0, v[184:185]
	v_lshl_add_u64 v[0:1], v[0:1], 0, v[2:3]
	v_mul_f32_e32 v2, 0x4f800000, v6
	v_rndne_f32_e32 v2, v2
	v_mul_f32_e64 v3, |v2|, s48
	v_floor_f32_e32 v3, v3
	v_fma_f32 v4, v3, s49, |v2|
	v_cvt_u32_f32_e32 v4, v4
	v_cvt_u32_f32_e32 v3, v3
	v_ashrrev_i32_e32 v5, 31, v2
	v_xor_b32_e32 v2, v4, v5
	v_xor_b32_e32 v3, v3, v5
	v_sub_co_u32_e32 v2, vcc, v2, v5
	s_nop 1
	v_subb_co_u32_e32 v3, vcc, v3, v5, vcc
	v_add_co_u32_e32 v0, vcc, 0x62c000, v0
	s_nop 1
	v_addc_co_u32_e32 v1, vcc, 0, v1, vcc
	flat_atomic_add_x2 v[0:1], v[2:3]

; __device__ __forceinline__ float bf_round(float f) { return __uint_as_float(f2bf(f) << 16); }
; __device__ __forceinline__ void atomic_addq(i64* p, float v, float scale) { (void)__hip_atomic_fetch_add((unsigned long long*)p, (unsigned long long)(i64)__builtin_rintf(v * scale), __ATOMIC_RELAXED, __HIP_MEMORY_SCOPE_AGENT); }
; template <class Map>
; __device__ __forceinline__ void conv_item(const Frame& F, int it, const float* W, int K, int N, bf16_t* WT, const float* gk, int gmask, float gmul, const float* bk, i64* cs, i64* bw, Map map) {
;     ...
;             const int n = lane & 31, kh = lane >> 5; float sb = 0.f, sc = 0.f;
; #pragma unroll 8
;             for (int j = 0; j < 32; ++j) { const int kk = kh * 32 + j; const float w = scr[kk * 33 + n]; sb += bk[k0 + kk] * w; sc += bf_round(gk[(k0 + kk) & gmask] * gmul * w); }
;             { auto r = __builtin_amdgcn_permlane32_swap(__float_as_uint(sb), __float_as_uint(sb), false, false); sb = __uint_as_float(r[0]) + __uint_as_float(r[1]); }
;             { auto r = __builtin_amdgcn_permlane32_swap(__float_as_uint(sc), __float_as_uint(sc), false, false); sc = __uint_as_float(r[0]) + __uint_as_float(r[1]); }
;             if (lane < 32) { atomic_addq(bw + v0 + n, sb, FX_COL); atomic_addq(cs + v0 + n, sc, FX_COL); }
.LBB0_1443:
	v_lshl_add_u64 v[132:133], v[6:7], 0, s[12:13]
	global_load_dword v134, v[132:133], off
	v_and_b32_e32 v135, 0x7f8, v28
	v_lshlrev_b32_e32 v135, 2, v135
	global_load_dword v136, v135, s[86:87]
	v_lshl_add_u64 v[138:139], v[8:9], 0, s[12:13]
	global_load_dwordx3 v[140:142], v[138:139], off offset:20
	v_lshl_add_u64 v[144:145], v[8:9], 0, s[12:13]
	global_load_dwordx4 v[148:151], v[144:145], off offset:4
	v_lshl_add_u64 v[146:147], v[10:11], 0, s[12:13]
	global_load_dword v137, v[146:147], off offset:4
	v_add_u32_e32 v143, 2, v28
	v_and_b32_e32 v152, 0x7fa, v143
	v_lshlrev_b32_e32 v152, 2, v152
	global_load_dword v153, v152, s[86:87]
	v_lshl_add_u64 v[154:155], v[10:11], 0, s[12:13]
	global_load_dword v156, v[154:155], off offset:12
	v_add_u32_e32 v157, 4, v28
	v_and_b32_e32 v158, 0x7fc, v157
	v_lshlrev_b32_e32 v158, 2, v158
	global_load_dword v159, v158, s[86:87]
	v_lshl_add_u64 v[160:161], v[10:11], 0, s[12:13]
	global_load_dword v162, v[160:161], off offset:20
	v_add_u32_e32 v163, 6, v28
	v_and_b32_e32 v164, 0x7fe, v163
	v_lshlrev_b32_e32 v164, 2, v164
	global_load_dword v165, v164, s[86:87]
	v_lshl_add_u64 v[166:167], v[10:11], 0, s[12:13]
	global_load_dword v168, v[166:167], off offset:28
	s_waitcnt vmcnt(0)
	v_lshl_add_u64 v[12:13], v[6:7], 0, s[12:13]
	ds_read2_b32 v[34:35], v29 offset1:33
	v_add_u32_e32 v38, 2, v28
	s_waitcnt vmcnt(0) lgkmcnt(0)
	v_mul_f32_e32 v12, v34, v134
	v_and_b32_e32 v2, 0x7f8, v28
	v_lshlrev_b32_e32 v2, 2, v2
	s_waitcnt vmcnt(0)
	v_mul_f32_e32 v2, v34, v136
	v_bfe_u32 v13, v2, 16, 1
	v_add3_u32 v2, v2, v13, s73
	v_and_b32_e32 v13, 0xffff0000, v2
	v_pk_add_f32 v[36:37], v[0:1], v[12:13]
	v_lshl_add_u64 v[12:13], v[8:9], 0, s[12:13]
	v_lshl_add_u64 v[12:13], v[10:11], 0, s[12:13]
	s_add_u32 s12, s12, 32
	s_addc_u32 s13, s13, 0
	s_cmpk_eq_i32 s12, 0x80
	s_waitcnt vmcnt(0)
	v_mul_f32_e32 v34, v35, v148
	s_waitcnt vmcnt(0)
	v_mul_f32_e32 v30, v35, v137
	v_bfe_u32 v35, v30, 16, 1
	v_add3_u32 v30, v30, v35, s73
	v_and_b32_e32 v35, 0xffff0000, v30
	v_pk_add_f32 v[34:35], v[36:37], v[34:35]
	ds_read2_b32 v[36:37], v29 offset0:66 offset1:99
	s_waitcnt lgkmcnt(0)
	v_mul_f32_e32 v30, v36, v149
	v_and_b32_e32 v31, 0x7fa, v38
	v_lshlrev_b32_e32 v31, 2, v31
	s_waitcnt vmcnt(0)
	v_mul_f32_e32 v31, v36, v153
	v_bfe_u32 v36, v31, 16, 1
	v_add3_u32 v31, v31, v36, s73
	v_and_b32_e32 v31, 0xffff0000, v31
	v_pk_add_f32 v[30:31], v[34:35], v[30:31]
	v_mul_f32_e32 v34, v37, v150
	v_add_u32_e32 v36, 4, v28
	s_waitcnt vmcnt(0)
	v_mul_f32_e32 v32, v37, v156
	v_bfe_u32 v35, v32, 16, 1
	v_add3_u32 v32, v32, v35, s73
	v_and_b32_e32 v35, 0xffff0000, v32
	v_pk_add_f32 v[30:31], v[30:31], v[34:35]
	ds_read2_b32 v[34:35], v29 offset0:132 offset1:165
	s_waitcnt lgkmcnt(0)
	v_mul_f32_e32 v32, v34, v151
	v_and_b32_e32 v33, 0x7fc, v36
	v_lshlrev_b32_e32 v33, 2, v33
	s_waitcnt vmcnt(0)
	v_mul_f32_e32 v33, v34, v159
	v_bfe_u32 v34, v33, 16, 1
	v_add3_u32 v33, v33, v34, s73
	v_and_b32_e32 v33, 0xffff0000, v33
	v_pk_add_f32 v[30:31], v[30:31], v[32:33]
	v_mul_f32_e32 v32, v35, v140
	v_add_u32_e32 v34, 6, v28
	v_add_u32_e32 v28, 8, v28
	s_waitcnt vmcnt(0)
	v_mul_f32_e32 v0, v35, v162
	v_bfe_u32 v33, v0, 16, 1
	v_add3_u32 v0, v0, v33, s73
	v_and_b32_e32 v33, 0xffff0000, v0
	v_pk_add_f32 v[30:31], v[30:31], v[32:33]
	ds_read2_b32 v[32:33], v29 offset0:198 offset1:231
	v_add_u32_e32 v29, 0x420, v29
	s_waitcnt lgkmcnt(0)
	v_mul_f32_e32 v0, v32, v141
	v_and_b32_e32 v1, 0x7fe, v34
	v_lshlrev_b32_e32 v1, 2, v1
	s_waitcnt vmcnt(0)
	v_mul_f32_e32 v1, v32, v165
	v_bfe_u32 v32, v1, 16, 1
	v_add3_u32 v1, v1, v32, s73
	v_and_b32_e32 v1, 0xffff0000, v1
	v_pk_add_f32 v[0:1], v[30:31], v[0:1]
	v_mul_f32_e32 v30, v33, v142
	s_waitcnt vmcnt(0)
	v_mul_f32_e32 v2, v33, v168
	v_bfe_u32 v12, v2, 16, 1
	v_add3_u32 v2, v2, v12, s73
	v_and_b32_e32 v31, 0xffff0000, v2
	v_pk_add_f32 v[0:1], v[0:1], v[30:31]
	s_cbranch_scc0 .LBB0_1443
	v_mov_b32_e32 v2, v0
	v_mov_b32_e32 v6, v1
	s_nop 0
	v_permlane32_swap_b32_e32 v0, v2
	v_permlane32_swap_b32_e32 v1, v6
	v_cmp_gt_u32_e32 vcc, 32, v5
	s_and_saveexec_b64 s[12:13], vcc
	s_cbranch_execz .LBB0_1446
	v_readlane_b32 s16, v255, 60
	v_readlane_b32 s17, v255, 61
	s_lshl_b64 s[16:17], s[16:17], 3
	s_add_u32 s42, s48, s16
	s_addc_u32 s43, s49, s17
	s_add_u32 s16, s96, s16
	v_add_f32_e32 v2, v0, v2
	v_ashrrev_i32_e32 v5, 31, v4
	s_addc_u32 s17, s97, s17
	v_add_f32_e32 v10, v1, v6
	v_lshlrev_b64 v[0:1], 3, v[4:5]
	v_mul_f32_e32 v2, 0x4f800000, v2
	v_lshl_add_u64 v[6:7], s[16:17], 0, v[0:1]
	v_rndne_f32_e32 v2, v2
	s_mov_b32 s16, 0x2f800000
	v_mul_f32_e64 v5, |v2|, s16
	v_floor_f32_e32 v5, v5
	s_mov_b32 s17, 0xcf800000
	v_fma_f32 v8, v5, s17, |v2|
	v_cvt_u32_f32_e32 v8, v8
	v_cvt_u32_f32_e32 v5, v5
	v_ashrrev_i32_e32 v2, 31, v2
	v_lshlrev_b32_e32 v184, 3, v27
	v_xor_b32_e32 v8, v8, v2
	v_xor_b32_e32 v5, v5, v2
	v_sub_co_u32_e32 v8, vcc, v8, v2
	v_lshl_add_u64 v[6:7], v[6:7], 0, v[184:185]
	s_nop 0
	v_subb_co_u32_e32 v9, vcc, v5, v2, vcc
	v_mul_f32_e32 v2, 0x4f800000, v10
	s_mov_b32 s48, 0x616000
	v_rndne_f32_e32 v2, v2
	v_add_co_u32_e32 v6, vcc, s48, v6
	v_mul_f32_e64 v5, |v2|, s16
	s_nop 0
	v_addc_co_u32_e32 v7, vcc, 0, v7, vcc
	v_floor_f32_e32 v5, v5
	flat_atomic_add_x2 v[6:7], v[8:9]
	v_fma_f32 v6, v5, s17, |v2|
	v_cvt_u32_f32_e32 v6, v6
	v_cvt_u32_f32_e32 v5, v5
	v_ashrrev_i32_e32 v2, 31, v2
	v_lshl_add_u64 v[0:1], s[42:43], 0, v[0:1]
	v_xor_b32_e32 v6, v6, v2
	v_xor_b32_e32 v5, v5, v2
	v_sub_co_u32_e32 v6, vcc, v6, v2
	v_lshl_add_u64 v[0:1], v[0:1], 0, v[184:185]
	s_nop 0
	v_subb_co_u32_e32 v7, vcc, v5, v2, vcc
	v_add_co_u32_e32 v0, vcc, 0x600000, v0
	s_nop 1
	v_addc_co_u32_e32 v1, vcc, 0, v1, vcc
	flat_atomic_add_x2 v[0:1], v[6:7]

; __device__ __forceinline__ float bf_round(float f) { return __uint_as_float(f2bf(f) << 16); }
; __device__ __forceinline__ void atomic_addq(i64* p, float v, float scale) { (void)__hip_atomic_fetch_add((unsigned long long*)p, (unsigned long long)(i64)__builtin_rintf(v * scale), __ATOMIC_RELAXED, __HIP_MEMORY_SCOPE_AGENT); }
; template <class Map>
; __device__ __forceinline__ void conv_item(const Frame& F, int it, const float* W, int K, int N, bf16_t* WT, const float* gk, int gmask, float gmul, const float* bk, i64* cs, i64* bw, Map map) {
;     ...
;             const int n = lane & 31, kh = lane >> 5; float sb = 0.f, sc = 0.f;
; #pragma unroll 8
;             for (int j = 0; j < 32; ++j) { const int kk = kh * 32 + j; const float w = scr[kk * 33 + n]; sb += bk[k0 + kk] * w; sc += bf_round(gk[(k0 + kk) & gmask] * gmul * w); }
;             { auto r = __builtin_amdgcn_permlane32_swap(__float_as_uint(sb), __float_as_uint(sb), false, false); sb = __uint_as_float(r[0]) + __uint_as_float(r[1]); }
;             { auto r = __builtin_amdgcn_permlane32_swap(__float_as_uint(sc), __float_as_uint(sc), false, false); sc = __uint_as_float(r[0]) + __uint_as_float(r[1]); }
;             if (lane < 32) { atomic_addq(bw + v0 + n, sb, FX_COL); atomic_addq(cs + v0 + n, sc, FX_COL); }
.LBB0_1658:
	v_lshl_add_u64 v[132:133], v[6:7], 0, s[78:79]
	v_add_co_u32_e32 v132, vcc, 0x2000, v132
	v_addc_co_u32_e32 v133, vcc, 0, v133, vcc
	global_load_dwordx4 v[136:139], v[132:133], off
	v_lshl_add_u64 v[134:135], v[6:7], 0, s[78:79]
	v_lshl_add_u64 v[140:141], v[134:135], 0, s[86:87]
	global_load_dwordx4 v[144:147], v[140:141], off offset:16
	v_and_b32_e32 v142, 0x7f8, v27
	v_lshlrev_b32_e32 v142, 2, v142
	global_load_dword v143, v142, s[96:97]
	v_lshl_add_u64 v[148:149], v[4:5], 0, s[78:79]
	v_add_co_u32_e32 v148, vcc, s16, v148
	v_addc_co_u32_e32 v149, vcc, 0, v149, vcc
	global_load_dword v150, v[148:149], off offset:4
	v_add_u32_e32 v151, 2, v27
	v_and_b32_e32 v151, 0x7fa, v151
	v_lshlrev_b32_e32 v151, 2, v151
	global_load_dword v152, v151, s[96:97]
	v_lshl_add_u64 v[154:155], v[4:5], 0, s[78:79]
	v_add_co_u32_e32 v154, vcc, s16, v154
	v_addc_co_u32_e32 v155, vcc, 0, v155, vcc
	global_load_dword v153, v[154:155], off offset:12
	v_add_u32_e32 v156, 4, v27
	v_and_b32_e32 v157, 0x7fc, v156
	v_lshlrev_b32_e32 v157, 2, v157
	global_load_dword v158, v157, s[96:97]
	v_lshl_add_u64 v[160:161], v[4:5], 0, s[78:79]
	v_add_co_u32_e32 v160, vcc, s16, v160
	v_addc_co_u32_e32 v161, vcc, 0, v161, vcc
	global_load_dword v159, v[160:161], off offset:20
	v_add_u32_e32 v162, 6, v27
	v_and_b32_e32 v163, 0x7fe, v162
	v_lshlrev_b32_e32 v163, 2, v163
	global_load_dword v164, v163, s[96:97]
	v_lshl_add_u64 v[166:167], v[4:5], 0, s[78:79]
	v_add_co_u32_e32 v166, vcc, s16, v166
	v_addc_co_u32_e32 v167, vcc, 0, v167, vcc
	global_load_dword v165, v[166:167], off offset:28
	s_waitcnt vmcnt(0)
	v_lshl_add_u64 v[0:1], v[6:7], 0, s[78:79]
	v_lshl_add_u64 v[2:3], v[0:1], 0, s[86:87]
	v_add_co_u32_e32 v0, vcc, 0x2000, v0
	v_and_b32_e32 v29, 0x7f8, v27
	s_nop 0
	v_addc_co_u32_e32 v1, vcc, 0, v1, vcc
	v_lshlrev_b32_e32 v29, 2, v29
	ds_read2_b32 v[34:35], v28 offset1:33
	s_nop 0
	s_waitcnt vmcnt(1) lgkmcnt(0)
	v_mul_f32_e32 v36, v34, v136
	s_waitcnt vmcnt(0)
	v_mul_f32_e32 v29, v34, v143
	v_bfe_u32 v30, v29, 16, 1
	v_add3_u32 v29, v29, v30, s73
	v_and_b32_e32 v37, 0xffff0000, v29
	v_pk_add_f32 v[36:37], v[10:11], v[36:37]
	v_lshl_add_u64 v[10:11], v[4:5], 0, s[78:79]
	v_add_co_u32_e32 v10, vcc, s16, v10
	v_mul_f32_e32 v30, v35, v137
	s_nop 0
	v_addc_co_u32_e32 v11, vcc, 0, v11, vcc
	s_add_u32 s78, s78, 32
	s_addc_u32 s79, s79, 0
	s_cmpk_eq_i32 s78, 0x80
	s_waitcnt vmcnt(0)
	v_mul_f32_e32 v29, v35, v150
	v_bfe_u32 v31, v29, 16, 1
	v_add3_u32 v29, v29, v31, s73
	v_and_b32_e32 v31, 0xffff0000, v29
	v_add_u32_e32 v29, 2, v27
	v_and_b32_e32 v29, 0x7fa, v29
	v_lshlrev_b32_e32 v29, 2, v29
	ds_read2_b32 v[34:35], v28 offset0:66 offset1:99
	v_pk_add_f32 v[30:31], v[36:37], v[30:31]
	s_waitcnt lgkmcnt(0)
	v_mul_f32_e32 v36, v34, v138
	s_waitcnt vmcnt(0)
	v_mul_f32_e32 v29, v34, v152
	v_bfe_u32 v32, v29, 16, 1
	v_add3_u32 v29, v29, v32, s73
	v_and_b32_e32 v37, 0xffff0000, v29
	v_mul_f32_e32 v32, v35, v139
	v_pk_add_f32 v[30:31], v[30:31], v[36:37]
	s_waitcnt vmcnt(0)
	v_mul_f32_e32 v29, v35, v153
	v_bfe_u32 v33, v29, 16, 1
	v_add3_u32 v29, v29, v33, s73
	v_and_b32_e32 v33, 0xffff0000, v29
	v_pk_add_f32 v[30:31], v[30:31], v[32:33]
	ds_read2_b32 v[32:33], v28 offset0:132 offset1:165
	v_add_u32_e32 v29, 4, v27
	s_waitcnt lgkmcnt(0)
	v_mul_f32_e32 v34, v32, v144
	v_and_b32_e32 v0, 0x7fc, v29
	v_lshlrev_b32_e32 v0, 2, v0
	s_waitcnt vmcnt(0)
	v_mul_f32_e32 v0, v32, v158
	v_bfe_u32 v29, v0, 16, 1
	v_add3_u32 v0, v0, v29, s73
	v_and_b32_e32 v35, 0xffff0000, v0
	v_mul_f32_e32 v0, v33, v145
	v_pk_add_f32 v[30:31], v[30:31], v[34:35]
	s_waitcnt vmcnt(0)
	v_mul_f32_e32 v1, v33, v159
	v_bfe_u32 v29, v1, 16, 1
	v_add3_u32 v1, v1, v29, s73
	v_and_b32_e32 v1, 0xffff0000, v1
	v_pk_add_f32 v[0:1], v[30:31], v[0:1]
	ds_read2_b32 v[30:31], v28 offset0:198 offset1:231
	v_add_u32_e32 v29, 6, v27
	v_add_u32_e32 v28, 0x420, v28
	v_add_u32_e32 v27, 8, v27
	s_waitcnt lgkmcnt(0)
	v_mul_f32_e32 v32, v30, v146
	v_and_b32_e32 v2, 0x7fe, v29
	v_lshlrev_b32_e32 v2, 2, v2
	s_waitcnt vmcnt(0)
	v_mul_f32_e32 v2, v30, v164
	v_bfe_u32 v29, v2, 16, 1
	v_add3_u32 v2, v2, v29, s73
	v_and_b32_e32 v33, 0xffff0000, v2
	v_mul_f32_e32 v2, v31, v147
	v_pk_add_f32 v[0:1], v[0:1], v[32:33]
	s_waitcnt vmcnt(0)
	v_mul_f32_e32 v3, v31, v165
	v_bfe_u32 v10, v3, 16, 1
	v_add3_u32 v3, v3, v10, s73
	v_and_b32_e32 v3, 0xffff0000, v3
	v_pk_add_f32 v[10:11], v[0:1], v[2:3]
	s_cbranch_scc0 .LBB0_1658
	v_mov_b32_e32 v0, v10
	v_mov_b32_e32 v1, v11
	s_nop 0
	v_permlane32_swap_b32_e32 v10, v0
	v_permlane32_swap_b32_e32 v11, v1
	v_cmp_gt_u32_e32 vcc, 32, v25
	s_and_saveexec_b64 s[16:17], vcc
	s_cbranch_execz .LBB0_1661
	v_readlane_b32 s78, v255, 58
	v_readlane_b32 s79, v255, 59
	v_add_f32_e32 v4, v10, v0
	s_lshl_b64 s[78:79], s[78:79], 3
	v_mul_f32_e32 v4, 0x4f800000, v4
	s_add_u32 s48, s48, s78
	v_rndne_f32_e32 v4, v4
	s_mov_b32 s21, 0x2f800000
	s_addc_u32 s49, s49, s79
	v_lshlrev_b32_e32 v184, 3, v8
	v_mul_f32_e64 v5, |v4|, s21
	v_add_f32_e32 v6, v11, v1
	v_lshl_add_u64 v[0:1], s[48:49], 0, v[184:185]
	v_floor_f32_e32 v5, v5
	s_mov_b32 s48, 0xcf800000
	v_fma_f32 v7, v5, s48, |v4|
	v_cvt_u32_f32_e32 v7, v7
	v_cvt_u32_f32_e32 v5, v5
	v_ashrrev_i32_e32 v10, 31, v4
	v_lshlrev_b32_e32 v2, 3, v26
	v_xor_b32_e32 v4, v7, v10
	v_mov_b32_e32 v3, v185
	v_xor_b32_e32 v5, v5, v10
	v_sub_co_u32_e32 v4, vcc, v4, v10
	v_lshl_add_u64 v[0:1], v[0:1], 0, v[2:3]
	s_nop 0
	v_subb_co_u32_e32 v5, vcc, v5, v10, vcc
	s_mov_b32 s49, 0x630000
	s_add_u32 s12, s12, s78
	v_add_co_u32_e32 v0, vcc, s49, v0
	s_addc_u32 s13, s13, s79
	s_nop 0
	v_addc_co_u32_e32 v1, vcc, 0, v1, vcc
	flat_atomic_add_x2 v[0:1], v[4:5]
	v_lshl_add_u64 v[0:1], s[12:13], 0, v[184:185]
	v_lshl_add_u64 v[0:1], v[0:1], 0, v[2:3]
	v_mul_f32_e32 v2, 0x4f800000, v6
	v_rndne_f32_e32 v2, v2
	v_mul_f32_e64 v3, |v2|, s21
	v_floor_f32_e32 v3, v3
	v_fma_f32 v4, v3, s48, |v2|
	v_cvt_u32_f32_e32 v4, v4
	v_cvt_u32_f32_e32 v3, v3
	v_ashrrev_i32_e32 v5, 31, v2
	v_xor_b32_e32 v2, v4, v5
	v_xor_b32_e32 v3, v3, v5
	v_sub_co_u32_e32 v2, vcc, v2, v5
	s_nop 1
	v_subb_co_u32_e32 v3, vcc, v3, v5, vcc
	v_add_co_u32_e32 v0, vcc, 0x62c000, v0
	s_nop 1
	v_addc_co_u32_e32 v1, vcc, 0, v1, vcc
	flat_atomic_add_x2 v[0:1], v[2:3]

; __device__ __forceinline__ float bf_round(float f) { return __uint_as_float(f2bf(f) << 16); }
; __device__ __forceinline__ void atomic_addq(i64* p, float v, float scale) { (void)__hip_atomic_fetch_add((unsigned long long*)p, (unsigned long long)(i64)__builtin_rintf(v * scale), __ATOMIC_RELAXED, __HIP_MEMORY_SCOPE_AGENT); }
; template <class Map>
; __device__ __forceinline__ void conv_item(const Frame& F, int it, const float* W, int K, int N, bf16_t* WT, const float* gk, int gmask, float gmul, const float* bk, i64* cs, i64* bw, Map map) {
;     ...
;             const int n = lane & 31, kh = lane >> 5; float sb = 0.f, sc = 0.f;
; #pragma unroll 8
;             for (int j = 0; j < 32; ++j) { const int kk = kh * 32 + j; const float w = scr[kk * 33 + n]; sb += bk[k0 + kk] * w; sc += bf_round(gk[(k0 + kk) & gmask] * gmul * w); }
;             { auto r = __builtin_amdgcn_permlane32_swap(__float_as_uint(sb), __float_as_uint(sb), false, false); sb = __uint_as_float(r[0]) + __uint_as_float(r[1]); }
;             { auto r = __builtin_amdgcn_permlane32_swap(__float_as_uint(sc), __float_as_uint(sc), false, false); sc = __uint_as_float(r[0]) + __uint_as_float(r[1]); }
;             if (lane < 32) { atomic_addq(bw + v0 + n, sb, FX_COL); atomic_addq(cs + v0 + n, sc, FX_COL); }
.LBB0_1669:
	v_lshl_add_u64 v[132:133], v[6:7], 0, s[42:43]
	global_load_dword v134, v[132:133], off
	v_and_b32_e32 v135, 0x7f8, v28
	v_lshlrev_b32_e32 v135, 2, v135
	global_load_dword v136, v135, s[92:93]
	v_lshl_add_u64 v[138:139], v[8:9], 0, s[42:43]
	global_load_dwordx3 v[140:142], v[138:139], off offset:20
	v_lshl_add_u64 v[144:145], v[8:9], 0, s[42:43]
	global_load_dwordx4 v[148:151], v[144:145], off offset:4
	v_lshl_add_u64 v[146:147], v[10:11], 0, s[42:43]
	global_load_dword v137, v[146:147], off offset:4
	v_add_u32_e32 v143, 2, v28
	v_and_b32_e32 v152, 0x7fa, v143
	v_lshlrev_b32_e32 v152, 2, v152
	global_load_dword v153, v152, s[92:93]
	v_lshl_add_u64 v[154:155], v[10:11], 0, s[42:43]
	global_load_dword v156, v[154:155], off offset:12
	v_add_u32_e32 v157, 4, v28
	v_and_b32_e32 v158, 0x7fc, v157
	v_lshlrev_b32_e32 v158, 2, v158
	global_load_dword v159, v158, s[92:93]
	v_lshl_add_u64 v[160:161], v[10:11], 0, s[42:43]
	global_load_dword v162, v[160:161], off offset:20
	v_add_u32_e32 v163, 6, v28
	v_and_b32_e32 v164, 0x7fe, v163
	v_lshlrev_b32_e32 v164, 2, v164
	global_load_dword v165, v164, s[92:93]
	v_lshl_add_u64 v[166:167], v[10:11], 0, s[42:43]
	global_load_dword v168, v[166:167], off offset:28
	s_waitcnt vmcnt(0)
	v_lshl_add_u64 v[12:13], v[6:7], 0, s[42:43]
	ds_read2_b32 v[34:35], v29 offset1:33
	v_add_u32_e32 v38, 2, v28
	s_waitcnt vmcnt(0) lgkmcnt(0)
	v_mul_f32_e32 v12, v34, v134
	v_and_b32_e32 v2, 0x7f8, v28
	v_lshlrev_b32_e32 v2, 2, v2
	s_waitcnt vmcnt(0)
	v_mul_f32_e32 v2, v34, v136
	v_bfe_u32 v13, v2, 16, 1
	v_add3_u32 v2, v2, v13, s73
	v_and_b32_e32 v13, 0xffff0000, v2
	v_pk_add_f32 v[36:37], v[0:1], v[12:13]
	v_lshl_add_u64 v[12:13], v[8:9], 0, s[42:43]
	v_lshl_add_u64 v[12:13], v[10:11], 0, s[42:43]
	s_add_u32 s42, s42, 32
	s_addc_u32 s43, s43, 0
	s_cmpk_eq_i32 s42, 0x80
	s_waitcnt vmcnt(0)
	v_mul_f32_e32 v34, v35, v148
	s_waitcnt vmcnt(0)
	v_mul_f32_e32 v30, v35, v137
	v_bfe_u32 v35, v30, 16, 1
	v_add3_u32 v30, v30, v35, s73
	v_and_b32_e32 v35, 0xffff0000, v30
	v_pk_add_f32 v[34:35], v[36:37], v[34:35]
	ds_read2_b32 v[36:37], v29 offset0:66 offset1:99
	s_waitcnt lgkmcnt(0)
	v_mul_f32_e32 v30, v36, v149
	v_and_b32_e32 v31, 0x7fa, v38
	v_lshlrev_b32_e32 v31, 2, v31
	s_waitcnt vmcnt(0)
	v_mul_f32_e32 v31, v36, v153
	v_bfe_u32 v36, v31, 16, 1
	v_add3_u32 v31, v31, v36, s73
	v_and_b32_e32 v31, 0xffff0000, v31
	v_pk_add_f32 v[30:31], v[34:35], v[30:31]
	v_mul_f32_e32 v34, v37, v150
	v_add_u32_e32 v36, 4, v28
	s_waitcnt vmcnt(0)
	v_mul_f32_e32 v32, v37, v156
	v_bfe_u32 v35, v32, 16, 1
	v_add3_u32 v32, v32, v35, s73
	v_and_b32_e32 v35, 0xffff0000, v32
	v_pk_add_f32 v[30:31], v[30:31], v[34:35]
	ds_read2_b32 v[34:35], v29 offset0:132 offset1:165
	s_waitcnt lgkmcnt(0)
	v_mul_f32_e32 v32, v34, v151
	v_and_b32_e32 v33, 0x7fc, v36
	v_lshlrev_b32_e32 v33, 2, v33
	s_waitcnt vmcnt(0)
	v_mul_f32_e32 v33, v34, v159
	v_bfe_u32 v34, v33, 16, 1
	v_add3_u32 v33, v33, v34, s73
	v_and_b32_e32 v33, 0xffff0000, v33
	v_pk_add_f32 v[30:31], v[30:31], v[32:33]
	v_mul_f32_e32 v32, v35, v140
	v_add_u32_e32 v34, 6, v28
	v_add_u32_e32 v28, 8, v28
	s_waitcnt vmcnt(0)
	v_mul_f32_e32 v0, v35, v162
	v_bfe_u32 v33, v0, 16, 1
	v_add3_u32 v0, v0, v33, s73
	v_and_b32_e32 v33, 0xffff0000, v0
	v_pk_add_f32 v[30:31], v[30:31], v[32:33]
	ds_read2_b32 v[32:33], v29 offset0:198 offset1:231
	v_add_u32_e32 v29, 0x420, v29
	s_waitcnt lgkmcnt(0)
	v_mul_f32_e32 v0, v32, v141
	v_and_b32_e32 v1, 0x7fe, v34
	v_lshlrev_b32_e32 v1, 2, v1
	s_waitcnt vmcnt(0)
	v_mul_f32_e32 v1, v32, v165
	v_bfe_u32 v32, v1, 16, 1
	v_add3_u32 v1, v1, v32, s73
	v_and_b32_e32 v1, 0xffff0000, v1
	v_pk_add_f32 v[0:1], v[30:31], v[0:1]
	v_mul_f32_e32 v30, v33, v142
	s_waitcnt vmcnt(0)
	v_mul_f32_e32 v2, v33, v168
	v_bfe_u32 v12, v2, 16, 1
	v_add3_u32 v2, v2, v12, s73
	v_and_b32_e32 v31, 0xffff0000, v2
	v_pk_add_f32 v[0:1], v[0:1], v[30:31]
	s_cbranch_scc0 .LBB0_1669
	v_mov_b32_e32 v2, v0
	v_mov_b32_e32 v6, v1
	s_nop 0
	v_permlane32_swap_b32_e32 v0, v2
	v_permlane32_swap_b32_e32 v1, v6
	v_cmp_gt_u32_e32 vcc, 32, v5
	s_and_saveexec_b64 s[16:17], vcc
	s_cbranch_execz .LBB0_1672
	v_readlane_b32 s42, v255, 58
	v_readlane_b32 s43, v255, 59
	s_lshl_b64 s[42:43], s[42:43], 3
	s_add_u32 s12, s12, s42
	v_add_f32_e32 v2, v0, v2
	s_addc_u32 s13, s13, s43
	v_mul_f32_e32 v2, 0x4f800000, v2
	s_add_u32 s42, s48, s42
	v_ashrrev_i32_e32 v5, 31, v4
	v_rndne_f32_e32 v2, v2
	s_mov_b32 s21, 0x2f800000
	s_addc_u32 s43, s49, s43
	v_add_f32_e32 v10, v1, v6
	v_lshlrev_b64 v[0:1], 3, v[4:5]
	v_mul_f32_e64 v5, |v2|, s21
	v_lshl_add_u64 v[6:7], s[42:43], 0, v[0:1]
	v_floor_f32_e32 v5, v5
	s_mov_b32 s42, 0xcf800000
	v_fma_f32 v8, v5, s42, |v2|
	v_cvt_u32_f32_e32 v8, v8
	v_cvt_u32_f32_e32 v5, v5
	v_ashrrev_i32_e32 v2, 31, v2
	v_lshlrev_b32_e32 v184, 3, v27
	v_xor_b32_e32 v8, v8, v2
	v_xor_b32_e32 v5, v5, v2
	v_sub_co_u32_e32 v8, vcc, v8, v2
	v_lshl_add_u64 v[6:7], v[6:7], 0, v[184:185]
	s_nop 0
	v_subb_co_u32_e32 v9, vcc, v5, v2, vcc
	v_mul_f32_e32 v2, 0x4f800000, v10
	s_mov_b32 s43, 0x616000
	v_rndne_f32_e32 v2, v2
	v_add_co_u32_e32 v6, vcc, s43, v6
	v_mul_f32_e64 v5, |v2|, s21
	s_nop 0
	v_addc_co_u32_e32 v7, vcc, 0, v7, vcc
	v_floor_f32_e32 v5, v5
	flat_atomic_add_x2 v[6:7], v[8:9]
	v_fma_f32 v6, v5, s42, |v2|
	v_cvt_u32_f32_e32 v6, v6
	v_cvt_u32_f32_e32 v5, v5
	v_ashrrev_i32_e32 v2, 31, v2
	v_lshl_add_u64 v[0:1], s[12:13], 0, v[0:1]
	v_xor_b32_e32 v6, v6, v2
	v_xor_b32_e32 v5, v5, v2
	v_sub_co_u32_e32 v6, vcc, v6, v2
	v_lshl_add_u64 v[0:1], v[0:1], 0, v[184:185]
	s_nop 0
	v_subb_co_u32_e32 v7, vcc, v5, v2, vcc
	v_add_co_u32_e32 v0, vcc, 0x600000, v0
	s_nop 1
	v_addc_co_u32_e32 v1, vcc, 0, v1, vcc
	flat_atomic_add_x2 v[0:1], v[6:7]

; __device__ __forceinline__ float bf_round(float f) { return __uint_as_float(f2bf(f) << 16); }
; __device__ __forceinline__ void atomic_addq(i64* p, float v, float scale) { (void)__hip_atomic_fetch_add((unsigned long long*)p, (unsigned long long)(i64)__builtin_rintf(v * scale), __ATOMIC_RELAXED, __HIP_MEMORY_SCOPE_AGENT); }
; template <class Map>
; __device__ __forceinline__ void conv_item(const Frame& F, int it, const float* W, int K, int N, bf16_t* WT, const float* gk, int gmask, float gmul, const float* bk, i64* cs, i64* bw, Map map) {
;     ...
;             const int n = lane & 31, kh = lane >> 5; float sb = 0.f, sc = 0.f;
; #pragma unroll 8
;             for (int j = 0; j < 32; ++j) { const int kk = kh * 32 + j; const float w = scr[kk * 33 + n]; sb += bk[k0 + kk] * w; sc += bf_round(gk[(k0 + kk) & gmask] * gmul * w); }
;             { auto r = __builtin_amdgcn_permlane32_swap(__float_as_uint(sb), __float_as_uint(sb), false, false); sb = __uint_as_float(r[0]) + __uint_as_float(r[1]); }
;             { auto r = __builtin_amdgcn_permlane32_swap(__float_as_uint(sc), __float_as_uint(sc), false, false); sc = __uint_as_float(r[0]) + __uint_as_float(r[1]); }
;             if (lane < 32) { atomic_addq(bw + v0 + n, sb, FX_COL); atomic_addq(cs + v0 + n, sc, FX_COL); }
.LBB0_1972:
	v_lshl_add_u64 v[132:133], v[6:7], 0, s[70:71]
	v_add_co_u32_e32 v132, vcc, 0x2000, v132
	v_addc_co_u32_e32 v133, vcc, 0, v133, vcc
	global_load_dwordx4 v[136:139], v[132:133], off
	v_lshl_add_u64 v[134:135], v[6:7], 0, s[70:71]
	v_lshl_add_u64 v[140:141], v[134:135], 0, s[36:37]
	global_load_dwordx4 v[144:147], v[140:141], off offset:16
	v_and_b32_e32 v142, 0x7f8, v21
	v_lshlrev_b32_e32 v142, 2, v142
	global_load_dword v143, v142, s[38:39]
	v_lshl_add_u64 v[148:149], v[4:5], 0, s[70:71]
	v_add_co_u32_e32 v148, vcc, s16, v148
	v_addc_co_u32_e32 v149, vcc, 0, v149, vcc
	global_load_dword v150, v[148:149], off offset:4
	v_add_u32_e32 v151, 2, v21
	v_and_b32_e32 v151, 0x7fa, v151
	v_lshlrev_b32_e32 v151, 2, v151
	global_load_dword v152, v151, s[38:39]
	v_lshl_add_u64 v[154:155], v[4:5], 0, s[70:71]
	v_add_co_u32_e32 v154, vcc, s16, v154
	v_addc_co_u32_e32 v155, vcc, 0, v155, vcc
	global_load_dword v153, v[154:155], off offset:12
	v_add_u32_e32 v156, 4, v21
	v_and_b32_e32 v157, 0x7fc, v156
	v_lshlrev_b32_e32 v157, 2, v157
	global_load_dword v158, v157, s[38:39]
	v_lshl_add_u64 v[160:161], v[4:5], 0, s[70:71]
	v_add_co_u32_e32 v160, vcc, s16, v160
	v_addc_co_u32_e32 v161, vcc, 0, v161, vcc
	global_load_dword v159, v[160:161], off offset:20
	v_add_u32_e32 v162, 6, v21
	v_and_b32_e32 v163, 0x7fe, v162
	v_lshlrev_b32_e32 v163, 2, v163
	global_load_dword v164, v163, s[38:39]
	v_lshl_add_u64 v[166:167], v[4:5], 0, s[70:71]
	v_add_co_u32_e32 v166, vcc, s16, v166
	v_addc_co_u32_e32 v167, vcc, 0, v167, vcc
	global_load_dword v165, v[166:167], off offset:28
	s_waitcnt vmcnt(0)
	v_lshl_add_u64 v[0:1], v[6:7], 0, s[70:71]
	v_lshl_add_u64 v[2:3], v[0:1], 0, s[36:37]
	v_add_co_u32_e32 v0, vcc, 0x2000, v0
	v_and_b32_e32 v23, 0x7f8, v21
	s_nop 0
	v_addc_co_u32_e32 v1, vcc, 0, v1, vcc
	v_lshlrev_b32_e32 v23, 2, v23
	ds_read2_b32 v[28:29], v22 offset1:33
	s_nop 0
	s_waitcnt vmcnt(1) lgkmcnt(0)
	v_mul_f32_e32 v30, v28, v136
	s_waitcnt vmcnt(0)
	v_mul_f32_e32 v23, v28, v143
	v_bfe_u32 v24, v23, 16, 1
	v_add3_u32 v23, v23, v24, s73
	v_and_b32_e32 v31, 0xffff0000, v23
	v_pk_add_f32 v[30:31], v[10:11], v[30:31]
	v_lshl_add_u64 v[10:11], v[4:5], 0, s[70:71]
	v_add_co_u32_e32 v10, vcc, s16, v10
	v_mul_f32_e32 v24, v29, v137
	s_nop 0
	v_addc_co_u32_e32 v11, vcc, 0, v11, vcc
	s_add_u32 s70, s70, 32
	s_addc_u32 s71, s71, 0
	s_cmpk_eq_i32 s70, 0x80
	s_waitcnt vmcnt(0)
	v_mul_f32_e32 v23, v29, v150
	v_bfe_u32 v25, v23, 16, 1
	v_add3_u32 v23, v23, v25, s73
	v_and_b32_e32 v25, 0xffff0000, v23
	v_add_u32_e32 v23, 2, v21
	v_and_b32_e32 v23, 0x7fa, v23
	v_lshlrev_b32_e32 v23, 2, v23
	ds_read2_b32 v[28:29], v22 offset0:66 offset1:99
	v_pk_add_f32 v[24:25], v[30:31], v[24:25]
	s_waitcnt lgkmcnt(0)
	v_mul_f32_e32 v30, v28, v138
	s_waitcnt vmcnt(0)
	v_mul_f32_e32 v23, v28, v152
	v_bfe_u32 v26, v23, 16, 1
	v_add3_u32 v23, v23, v26, s73
	v_and_b32_e32 v31, 0xffff0000, v23
	v_mul_f32_e32 v26, v29, v139
	v_pk_add_f32 v[24:25], v[24:25], v[30:31]
	s_waitcnt vmcnt(0)
	v_mul_f32_e32 v23, v29, v153
	v_bfe_u32 v27, v23, 16, 1
	v_add3_u32 v23, v23, v27, s73
	v_and_b32_e32 v27, 0xffff0000, v23
	v_pk_add_f32 v[24:25], v[24:25], v[26:27]
	ds_read2_b32 v[26:27], v22 offset0:132 offset1:165
	v_add_u32_e32 v23, 4, v21
	s_waitcnt lgkmcnt(0)
	v_mul_f32_e32 v28, v26, v144
	v_and_b32_e32 v0, 0x7fc, v23
	v_lshlrev_b32_e32 v0, 2, v0
	s_waitcnt vmcnt(0)
	v_mul_f32_e32 v0, v26, v158
	v_bfe_u32 v23, v0, 16, 1
	v_add3_u32 v0, v0, v23, s73
	v_and_b32_e32 v29, 0xffff0000, v0
	v_mul_f32_e32 v0, v27, v145
	v_pk_add_f32 v[24:25], v[24:25], v[28:29]
	s_waitcnt vmcnt(0)
	v_mul_f32_e32 v1, v27, v159
	v_bfe_u32 v23, v1, 16, 1
	v_add3_u32 v1, v1, v23, s73
	v_and_b32_e32 v1, 0xffff0000, v1
	v_pk_add_f32 v[0:1], v[24:25], v[0:1]
	ds_read2_b32 v[24:25], v22 offset0:198 offset1:231
	v_add_u32_e32 v23, 6, v21
	v_add_u32_e32 v22, 0x420, v22
	v_add_u32_e32 v21, 8, v21
	s_waitcnt lgkmcnt(0)
	v_mul_f32_e32 v26, v24, v146
	v_and_b32_e32 v2, 0x7fe, v23
	v_lshlrev_b32_e32 v2, 2, v2
	s_waitcnt vmcnt(0)
	v_mul_f32_e32 v2, v24, v164
	v_bfe_u32 v23, v2, 16, 1
	v_add3_u32 v2, v2, v23, s73
	v_and_b32_e32 v27, 0xffff0000, v2
	v_mul_f32_e32 v2, v25, v147
	v_pk_add_f32 v[0:1], v[0:1], v[26:27]
	s_waitcnt vmcnt(0)
	v_mul_f32_e32 v3, v25, v165
	v_bfe_u32 v10, v3, 16, 1
	v_add3_u32 v3, v3, v10, s73
	v_and_b32_e32 v3, 0xffff0000, v3
	v_pk_add_f32 v[10:11], v[0:1], v[2:3]
	s_cbranch_scc0 .LBB0_1972
	v_mov_b32_e32 v0, v10
	v_mov_b32_e32 v1, v11
	s_nop 0
	v_permlane32_swap_b32_e32 v10, v0
	v_permlane32_swap_b32_e32 v11, v1
	v_cmp_gt_u32_e32 vcc, 32, v19
	s_and_saveexec_b64 s[16:17], vcc
	s_cbranch_execz .LBB0_1975
	v_add_f32_e32 v4, v10, v0
	v_mul_f32_e32 v4, 0x4f800000, v4
	v_rndne_f32_e32 v4, v4
	s_mov_b32 s36, 0x2f800000
	v_mul_f32_e64 v5, |v4|, s36
	v_floor_f32_e32 v5, v5
	s_mov_b32 s37, 0xcf800000
	v_fma_f32 v7, v5, s37, |v4|
	v_cvt_u32_f32_e32 v7, v7
	v_cvt_u32_f32_e32 v5, v5
	s_lshl_b64 s[70:71], s[60:61], 3
	s_add_u32 s48, s48, s70
	v_ashrrev_i32_e32 v10, 31, v4
	s_addc_u32 s49, s49, s71
	v_lshlrev_b32_e32 v184, 3, v8
	v_xor_b32_e32 v4, v7, v10
	v_add_f32_e32 v6, v11, v1
	v_lshl_add_u64 v[0:1], s[48:49], 0, v[184:185]
	v_lshlrev_b32_e32 v2, 3, v20
	v_mov_b32_e32 v3, v185
	v_xor_b32_e32 v5, v5, v10
	v_sub_co_u32_e32 v4, vcc, v4, v10
	v_lshl_add_u64 v[0:1], v[0:1], 0, v[2:3]
	s_nop 0
	v_subb_co_u32_e32 v5, vcc, v5, v10, vcc
	s_mov_b32 s48, 0x630000
	s_add_u32 s12, s12, s70
	v_add_co_u32_e32 v0, vcc, s48, v0
	s_addc_u32 s13, s13, s71
	s_nop 0
	v_addc_co_u32_e32 v1, vcc, 0, v1, vcc
	flat_atomic_add_x2 v[0:1], v[4:5]
	v_lshl_add_u64 v[0:1], s[12:13], 0, v[184:185]
	v_lshl_add_u64 v[0:1], v[0:1], 0, v[2:3]
	v_mul_f32_e32 v2, 0x4f800000, v6
	v_rndne_f32_e32 v2, v2
	v_mul_f32_e64 v3, |v2|, s36
	v_floor_f32_e32 v3, v3
	v_fma_f32 v4, v3, s37, |v2|
	v_cvt_u32_f32_e32 v4, v4
	v_cvt_u32_f32_e32 v3, v3
	v_ashrrev_i32_e32 v5, 31, v2
	v_xor_b32_e32 v2, v4, v5
	v_xor_b32_e32 v3, v3, v5
	v_sub_co_u32_e32 v2, vcc, v2, v5
	s_nop 1
	v_subb_co_u32_e32 v3, vcc, v3, v5, vcc
	v_add_co_u32_e32 v0, vcc, 0x62c000, v0
	s_nop 1
	v_addc_co_u32_e32 v1, vcc, 0, v1, vcc
	flat_atomic_add_x2 v[0:1], v[2:3]

; __device__ __forceinline__ float bf_round(float f) { return __uint_as_float(f2bf(f) << 16); }
; __device__ __forceinline__ void atomic_addq(i64* p, float v, float scale) { (void)__hip_atomic_fetch_add((unsigned long long*)p, (unsigned long long)(i64)__builtin_rintf(v * scale), __ATOMIC_RELAXED, __HIP_MEMORY_SCOPE_AGENT); }
; template <class Map>
; __device__ __forceinline__ void conv_item(const Frame& F, int it, const float* W, int K, int N, bf16_t* WT, const float* gk, int gmask, float gmul, const float* bk, i64* cs, i64* bw, Map map) {
;     ...
;             const int n = lane & 31, kh = lane >> 5; float sb = 0.f, sc = 0.f;
; #pragma unroll 8
;             for (int j = 0; j < 32; ++j) { const int kk = kh * 32 + j; const float w = scr[kk * 33 + n]; sb += bk[k0 + kk] * w; sc += bf_round(gk[(k0 + kk) & gmask] * gmul * w); }
;             { auto r = __builtin_amdgcn_permlane32_swap(__float_as_uint(sb), __float_as_uint(sb), false, false); sb = __uint_as_float(r[0]) + __uint_as_float(r[1]); }
;             { auto r = __builtin_amdgcn_permlane32_swap(__float_as_uint(sc), __float_as_uint(sc), false, false); sc = __uint_as_float(r[0]) + __uint_as_float(r[1]); }
;             if (lane < 32) { atomic_addq(bw + v0 + n, sb, FX_COL); atomic_addq(cs + v0 + n, sc, FX_COL); }
.LBB0_1983:
	v_lshl_add_u64 v[132:133], v[6:7], 0, s[38:39]
	global_load_dword v134, v[132:133], off
	v_and_b32_e32 v135, 0x7f8, v22
	v_lshlrev_b32_e32 v135, 2, v135
	global_load_dword v136, v135, s[30:31]
	v_lshl_add_u64 v[138:139], v[8:9], 0, s[38:39]
	global_load_dwordx3 v[140:142], v[138:139], off offset:20
	v_lshl_add_u64 v[144:145], v[8:9], 0, s[38:39]
	global_load_dwordx4 v[148:151], v[144:145], off offset:4
	v_lshl_add_u64 v[146:147], v[10:11], 0, s[38:39]
	global_load_dword v137, v[146:147], off offset:4
	v_add_u32_e32 v143, 2, v22
	v_and_b32_e32 v152, 0x7fa, v143
	v_lshlrev_b32_e32 v152, 2, v152
	global_load_dword v153, v152, s[30:31]
	v_lshl_add_u64 v[154:155], v[10:11], 0, s[38:39]
	global_load_dword v156, v[154:155], off offset:12
	v_add_u32_e32 v157, 4, v22
	v_and_b32_e32 v158, 0x7fc, v157
	v_lshlrev_b32_e32 v158, 2, v158
	global_load_dword v159, v158, s[30:31]
	v_lshl_add_u64 v[160:161], v[10:11], 0, s[38:39]
	global_load_dword v162, v[160:161], off offset:20
	v_add_u32_e32 v163, 6, v22
	v_and_b32_e32 v164, 0x7fe, v163
	v_lshlrev_b32_e32 v164, 2, v164
	global_load_dword v165, v164, s[30:31]
	v_lshl_add_u64 v[166:167], v[10:11], 0, s[38:39]
	global_load_dword v168, v[166:167], off offset:28
	s_waitcnt vmcnt(0)
	v_lshl_add_u64 v[12:13], v[6:7], 0, s[38:39]
	ds_read2_b32 v[28:29], v23 offset1:33
	v_add_u32_e32 v32, 2, v22
	s_waitcnt vmcnt(0) lgkmcnt(0)
	v_mul_f32_e32 v12, v28, v134
	v_and_b32_e32 v2, 0x7f8, v22
	v_lshlrev_b32_e32 v2, 2, v2
	s_waitcnt vmcnt(0)
	v_mul_f32_e32 v2, v28, v136
	v_bfe_u32 v13, v2, 16, 1
	v_add3_u32 v2, v2, v13, s73
	v_and_b32_e32 v13, 0xffff0000, v2
	v_pk_add_f32 v[30:31], v[0:1], v[12:13]
	v_lshl_add_u64 v[12:13], v[8:9], 0, s[38:39]
	v_lshl_add_u64 v[12:13], v[10:11], 0, s[38:39]
	s_add_u32 s38, s38, 32
	s_addc_u32 s39, s39, 0
	s_cmpk_eq_i32 s38, 0x80
	s_waitcnt vmcnt(0)
	v_mul_f32_e32 v28, v29, v148
	s_waitcnt vmcnt(0)
	v_mul_f32_e32 v24, v29, v137
	v_bfe_u32 v29, v24, 16, 1
	v_add3_u32 v24, v24, v29, s73
	v_and_b32_e32 v29, 0xffff0000, v24
	v_pk_add_f32 v[28:29], v[30:31], v[28:29]
	ds_read2_b32 v[30:31], v23 offset0:66 offset1:99
	s_waitcnt lgkmcnt(0)
	v_mul_f32_e32 v24, v30, v149
	v_and_b32_e32 v25, 0x7fa, v32
	v_lshlrev_b32_e32 v25, 2, v25
	s_waitcnt vmcnt(0)
	v_mul_f32_e32 v25, v30, v153
	v_bfe_u32 v30, v25, 16, 1
	v_add3_u32 v25, v25, v30, s73
	v_and_b32_e32 v25, 0xffff0000, v25
	v_pk_add_f32 v[24:25], v[28:29], v[24:25]
	v_mul_f32_e32 v28, v31, v150
	v_add_u32_e32 v30, 4, v22
	s_waitcnt vmcnt(0)
	v_mul_f32_e32 v26, v31, v156
	v_bfe_u32 v29, v26, 16, 1
	v_add3_u32 v26, v26, v29, s73
	v_and_b32_e32 v29, 0xffff0000, v26
	v_pk_add_f32 v[24:25], v[24:25], v[28:29]
	ds_read2_b32 v[28:29], v23 offset0:132 offset1:165
	s_waitcnt lgkmcnt(0)
	v_mul_f32_e32 v26, v28, v151
	v_and_b32_e32 v27, 0x7fc, v30
	v_lshlrev_b32_e32 v27, 2, v27
	s_waitcnt vmcnt(0)
	v_mul_f32_e32 v27, v28, v159
	v_bfe_u32 v28, v27, 16, 1
	v_add3_u32 v27, v27, v28, s73
	v_and_b32_e32 v27, 0xffff0000, v27
	v_pk_add_f32 v[24:25], v[24:25], v[26:27]
	v_mul_f32_e32 v26, v29, v140
	v_add_u32_e32 v28, 6, v22
	v_add_u32_e32 v22, 8, v22
	s_waitcnt vmcnt(0)
	v_mul_f32_e32 v0, v29, v162
	v_bfe_u32 v27, v0, 16, 1
	v_add3_u32 v0, v0, v27, s73
	v_and_b32_e32 v27, 0xffff0000, v0
	v_pk_add_f32 v[24:25], v[24:25], v[26:27]
	ds_read2_b32 v[26:27], v23 offset0:198 offset1:231
	v_add_u32_e32 v23, 0x420, v23
	s_waitcnt lgkmcnt(0)
	v_mul_f32_e32 v0, v26, v141
	v_and_b32_e32 v1, 0x7fe, v28
	v_lshlrev_b32_e32 v1, 2, v1
	s_waitcnt vmcnt(0)
	v_mul_f32_e32 v1, v26, v165
	v_bfe_u32 v26, v1, 16, 1
	v_add3_u32 v1, v1, v26, s73
	v_and_b32_e32 v1, 0xffff0000, v1
	v_pk_add_f32 v[0:1], v[24:25], v[0:1]
	v_mul_f32_e32 v24, v27, v142
	s_waitcnt vmcnt(0)
	v_mul_f32_e32 v2, v27, v168
	v_bfe_u32 v12, v2, 16, 1
	v_add3_u32 v2, v2, v12, s73
	v_and_b32_e32 v25, 0xffff0000, v2
	v_pk_add_f32 v[0:1], v[0:1], v[24:25]
	s_cbranch_scc0 .LBB0_1983
	v_mov_b32_e32 v2, v0
	v_mov_b32_e32 v6, v1
	s_nop 0
	v_permlane32_swap_b32_e32 v0, v2
	v_permlane32_swap_b32_e32 v1, v6
	v_cmp_gt_u32_e32 vcc, 32, v5
	s_and_saveexec_b64 s[16:17], vcc
	s_cbranch_execz .LBB0_1986
	s_lshl_b64 s[38:39], s[60:61], 3
	s_add_u32 s12, s12, s38
	s_addc_u32 s13, s13, s39
	s_add_u32 s38, s48, s38
	v_add_f32_e32 v2, v0, v2
	v_ashrrev_i32_e32 v5, 31, v4
	s_addc_u32 s39, s49, s39
	v_add_f32_e32 v10, v1, v6
	v_lshlrev_b64 v[0:1], 3, v[4:5]
	v_mul_f32_e32 v2, 0x4f800000, v2
	v_lshl_add_u64 v[6:7], s[38:39], 0, v[0:1]
	v_rndne_f32_e32 v2, v2
	s_mov_b32 s38, 0x2f800000
	v_mul_f32_e64 v5, |v2|, s38
	v_floor_f32_e32 v5, v5
	s_mov_b32 s39, 0xcf800000
	v_fma_f32 v8, v5, s39, |v2|
	v_cvt_u32_f32_e32 v8, v8
	v_cvt_u32_f32_e32 v5, v5
	v_ashrrev_i32_e32 v2, 31, v2
	v_lshlrev_b32_e32 v184, 3, v21
	v_xor_b32_e32 v8, v8, v2
	v_xor_b32_e32 v5, v5, v2
	v_sub_co_u32_e32 v8, vcc, v8, v2
	v_lshl_add_u64 v[6:7], v[6:7], 0, v[184:185]
	s_nop 0
	v_subb_co_u32_e32 v9, vcc, v5, v2, vcc
	v_mul_f32_e32 v2, 0x4f800000, v10
	s_mov_b32 s46, 0x616000
	v_rndne_f32_e32 v2, v2
	v_add_co_u32_e32 v6, vcc, s46, v6
	v_mul_f32_e64 v5, |v2|, s38
	s_nop 0
	v_addc_co_u32_e32 v7, vcc, 0, v7, vcc
	v_floor_f32_e32 v5, v5
	flat_atomic_add_x2 v[6:7], v[8:9]
	v_fma_f32 v6, v5, s39, |v2|
	v_cvt_u32_f32_e32 v6, v6
	v_cvt_u32_f32_e32 v5, v5
	v_ashrrev_i32_e32 v2, 31, v2
	v_lshl_add_u64 v[0:1], s[12:13], 0, v[0:1]
	v_xor_b32_e32 v6, v6, v2
	v_xor_b32_e32 v5, v5, v2
	v_sub_co_u32_e32 v6, vcc, v6, v2
	v_lshl_add_u64 v[0:1], v[0:1], 0, v[184:185]
	s_nop 0
	v_subb_co_u32_e32 v7, vcc, v5, v2, vcc
	v_add_co_u32_e32 v0, vcc, 0x600000, v0
	s_nop 1
	v_addc_co_u32_e32 v1, vcc, 0, v1, vcc
	flat_atomic_add_x2 v[0:1], v[6:7]
